# v62 + attention key loops (SWA x2, NSA window, NSA selected): K-fragment LDS reads and first three QK MFMAs moved ahead of the next-tile LDS commit and the tile-after-next prefetch issue (now in the M
# speedup vs baseline: 1.0003x; 1.0003x over previous
; #define MFMA(a, b, c) __builtin_amdgcn_mfma_f32_32x32x16_bf16((a), (b), (c), 0, 0, 0)
; template <int DQK, bool MASKED, int MODE, class MF>
; DI void attn_step(const bf16_t* sK, const bf16_t* sVt, const bf16x8 (&qf)[DQK / 16], f32x16& o0, f32x16& o1, float& m, float& l,
;                   float sc, const MF& mf, int lane, f32x16 (&s)[2], float invl, bool lanevalid = true) {
;     ...
; #pragma unroll
;   for (int sub = 0; sub < 2; ++sub)
; #pragma unroll
;     for (int ks = 0; ks < DQK / 16; ++ks) kf[sub][ks] = *(const bf16x8*)(sK + (sub * 32 + pr) * KST + ks * 16 + 8 * h);
;   __builtin_amdgcn_sched_barrier(0);
; #pragma unroll
;   for (int q = 0; q < 16; ++q) { s[0][q] = 0.f; s[1][q] = 0.f; }
; #pragma unroll
;   for (int ks = 0; ks < DQK / 16; ++ks) {
;     s[0] = MFMA(kf[0][ks], qf[ks], s[0]);
;     s[1] = MFMA(kf[1][ks], qf[ks], s[1]);
;   }
; DI void phase_attn_swa(const Params& P, const float* sinks, bf16_t* og, unsigned char* smem, int L, int G) {
;     ...
;     for (int j = jlo; j <= jhi; ++j) {
;       const int key0 = j * 64, cb = (j - jlo) & 1;
;       __syncthreads();
;       if (j < jhi) kv64_store(R, sK + (cb ^ 1) * KVB64, sVt + (cb ^ 1) * KVB64, tid);
;       if (j + 1 < jhi) kv64_fetch(R, kb, 256, vb, SEQ, key0 + 128, true, tid);
;       __builtin_amdgcn_sched_barrier(0);
;       auto mf = [&](int kk) { const int key = key0 + kk; return key <= t && key > t - 128; };
;       attn_step<64, true, 0>(sK + cb * KVB64, sVt + cb * KVB64, qf, o0, o1, m, l, sc, mf, lane, s, 0.f);
.LBB0_346:
	s_add_i32 s1, s46, s47
	s_and_b32 s0, s47, 1
	s_cmp_ge_u32 s1, s41
	s_cselect_b32 s99, 0, 1
	s_add_i32 s1, s1, 1
	s_cmp_ge_u32 s1, s41
	s_cselect_b32 s98, 0, 2
	s_or_b32 s99, s99, s98
	s_xor_b32 s98, s0, 1
	s_mulk_i32 s98, 0x4800
	s_waitcnt lgkmcnt(0)
	s_barrier
.LBB0_348:
.LBB0_350:
	s_mulk_i32 s0, 0x4800
	v_add_u32_e32 v40, s0, v163
	ds_read_b128 v[32:35], v40
	ds_read_b128 v[96:99], v40 offset:32
	ds_read_b128 v[100:103], v40 offset:64
	ds_read_b128 v[104:107], v40 offset:96
	ds_read_b128 v[36:39], v40 offset:4608
	ds_read_b128 v[108:111], v40 offset:4640
	ds_read_b128 v[112:115], v40 offset:4672
	ds_read_b128 v[178:181], v40 offset:4704
	v_add_u32_e32 v116, s0, v137
	s_waitcnt lgkmcnt(7)
	v_mfma_f32_32x32x16_bf16 v[48:63], v[32:35], v[64:67], 0
	s_waitcnt lgkmcnt(3)
	v_mfma_f32_32x32x16_bf16 v[32:47], v[36:39], v[64:67], 0
	v_mfma_f32_32x32x16_bf16 v[48:63], v[96:99], v[68:71], v[48:63]
	v_add3_u32 v96, v116, v164, v171
	v_add3_u32 v97, v116, v165, v171
	s_bitcmp1_b32 s99, 0
	s_cbranch_scc0 .Lmy_hm346_0_ns
	v_add_u32_e32 v247, s98, v160
	s_waitcnt vmcnt(3)
	ds_write_b128 v247, v[80:83]
	s_waitcnt vmcnt(2)
	ds_write_b128 v247, v[84:87] offset:4608
	s_waitcnt vmcnt(1)
	ds_write_b128 v247, v[88:91] offset:9216
	s_waitcnt vmcnt(0)
	ds_write_b128 v247, v[92:95] offset:13824
	s_branch .Lmy_hm346_0_sd
.Lmy_hm346_0_ns:
	ds_read_b32 v247, v160
	ds_read_b32 v247, v160
	ds_read_b32 v247, v160
	ds_read_b32 v247, v160
.Lmy_hm346_0_sd:
	s_bitcmp1_b32 s99, 1
	s_cbranch_scc0 .Lmy_hm346_0_np
	v_mov_b32_e32 v253, 0
	v_add_u32_e32 v250, s38, v158
	v_add_u32_e32 v252, 0x80, v250
	v_lshlrev_b64 v[248:249], 9, v[252:253]
	v_add_u32_e32 v252, 0xa0, v250
	v_lshl_add_u64 v[248:249], v[152:153], 0, v[248:249]
	v_lshlrev_b64 v[250:251], 9, v[252:253]
	s_lshl_b64 s[100:101], s[38:39], 1
	v_lshl_add_u64 v[250:251], v[152:153], 0, v[250:251]
	global_load_dwordx4 v[80:83], v[248:249], off
	global_load_dwordx4 v[84:87], v[250:251], off
	v_lshl_add_u64 v[248:249], v[154:155], 0, s[100:101]
	v_lshl_add_u64 v[250:251], v[156:157], 0, s[100:101]
	global_load_dwordx4 v[88:91], v[248:249], off offset:256
	global_load_dwordx4 v[92:95], v[250:251], off offset:256
.Lmy_hm346_0_np:
	s_waitcnt lgkmcnt(6)
	v_mfma_f32_32x32x16_bf16 v[32:47], v[108:111], v[68:71], v[32:47]
	v_mfma_f32_32x32x16_bf16 v[48:63], v[100:103], v[72:75], v[48:63]
	s_waitcnt lgkmcnt(5)
	v_mfma_f32_32x32x16_bf16 v[32:47], v[112:115], v[72:75], v[32:47]
	v_mfma_f32_32x32x16_bf16 v[48:63], v[104:107], v[76:79], v[48:63]
	ds_read_b128 v[124:127], v96 offset:9216
	ds_read_b128 v[116:119], v96 offset:9248
	ds_read_b128 v[120:123], v97 offset:9216
	ds_read_b128 v[112:115], v97 offset:9248
	ds_read_b128 v[108:111], v96 offset:9280
	ds_read_b128 v[100:103], v96 offset:9312
	ds_read_b128 v[104:107], v97 offset:9280
	ds_read_b128 v[96:99], v97 offset:9312
	s_waitcnt lgkmcnt(12)
	v_mfma_f32_32x32x16_bf16 v[32:47], v[178:181], v[76:79], v[32:47]
	v_add_u32_e32 v128, s38, v162
	v_cmp_le_u32_e32 vcc, v128, v150
	v_cmp_gt_i32_e64 s[0:1], v128, v151
	s_and_b64 vcc, vcc, s[0:1]
	v_cndmask_b32_e32 v48, v172, v48, vcc
	v_cmp_lt_u32_e32 vcc, v128, v150
	v_cmp_ge_i32_e64 s[0:1], v128, v151
	s_and_b64 vcc, vcc, s[0:1]
	v_add_u32_e32 v177, 2, v128
	v_cndmask_b32_e32 v49, v172, v49, vcc
	v_cmp_le_u32_e32 vcc, v177, v150
	v_cmp_gt_i32_e64 s[0:1], v177, v151
	s_and_b64 vcc, vcc, s[0:1]
	v_add_u32_e32 v177, 3, v128
	v_cndmask_b32_e32 v50, v172, v50, vcc
	v_cmp_le_u32_e32 vcc, v177, v150
	v_cmp_gt_i32_e64 s[0:1], v177, v151
	s_and_b64 vcc, vcc, s[0:1]
	v_add_u32_e32 v177, 4, v128
	v_cndmask_b32_e32 v51, v172, v51, vcc
	v_cmp_le_u32_e32 vcc, v177, v150
	v_cmp_gt_i32_e64 s[0:1], v177, v151
	s_and_b64 vcc, vcc, s[0:1]
	v_add_u32_e32 v177, 5, v128
	v_cndmask_b32_e32 v52, v172, v52, vcc
	v_cmp_le_u32_e32 vcc, v177, v150
	v_cmp_gt_i32_e64 s[0:1], v177, v151
	s_and_b64 vcc, vcc, s[0:1]
	v_add_u32_e32 v177, 6, v128
	v_cndmask_b32_e32 v53, v172, v53, vcc
	v_cmp_le_u32_e32 vcc, v177, v150
	v_cmp_gt_i32_e64 s[0:1], v177, v151
	v_add_u32_e32 v177, s38, v161
	s_and_b64 vcc, vcc, s[0:1]
	v_or_b32_e32 v178, 7, v177
	v_cndmask_b32_e32 v54, v172, v54, vcc
	v_cmp_le_u32_e32 vcc, v178, v150
	v_cmp_gt_i32_e64 s[0:1], v178, v151
	s_and_b64 vcc, vcc, s[0:1]
	v_add_u32_e32 v178, 16, v128
	v_cndmask_b32_e32 v55, v172, v55, vcc
	v_cmp_le_u32_e32 vcc, v178, v150
	v_cmp_gt_i32_e64 s[0:1], v178, v151
	s_and_b64 vcc, vcc, s[0:1]
	v_add_u32_e32 v178, 17, v128
	v_cndmask_b32_e32 v56, v172, v56, vcc
	v_cmp_le_u32_e32 vcc, v178, v150
	v_cmp_gt_i32_e64 s[0:1], v178, v151
	s_and_b64 vcc, vcc, s[0:1]
	v_add_u32_e32 v178, 18, v128
	v_cndmask_b32_e32 v57, v172, v57, vcc
	v_cmp_le_u32_e32 vcc, v178, v150
	v_cmp_gt_i32_e64 s[0:1], v178, v151
	s_and_b64 vcc, vcc, s[0:1]
	v_add_u32_e32 v178, 19, v128
	v_cndmask_b32_e32 v58, v172, v58, vcc
	v_cmp_le_u32_e32 vcc, v178, v150
	v_cmp_gt_i32_e64 s[0:1], v178, v151
	s_and_b64 vcc, vcc, s[0:1]
	v_add_u32_e32 v178, 20, v128
	v_cndmask_b32_e32 v59, v172, v59, vcc
	v_cmp_le_u32_e32 vcc, v178, v150
	v_cmp_gt_i32_e64 s[0:1], v178, v151
	s_and_b64 vcc, vcc, s[0:1]
	v_add_u32_e32 v178, 21, v128
	v_cndmask_b32_e32 v60, v172, v60, vcc
	v_cmp_le_u32_e32 vcc, v178, v150
	v_cmp_gt_i32_e64 s[0:1], v178, v151
	s_and_b64 vcc, vcc, s[0:1]
	v_add_u32_e32 v178, 22, v128
	v_cndmask_b32_e32 v61, v172, v61, vcc
	v_cmp_le_u32_e32 vcc, v178, v150
	v_cmp_gt_i32_e64 s[0:1], v178, v151
	s_and_b64 vcc, vcc, s[0:1]
	v_or_b32_e32 v178, 23, v177
	v_cndmask_b32_e32 v62, v172, v62, vcc
	v_cmp_le_u32_e32 vcc, v178, v150
	v_cmp_gt_i32_e64 s[0:1], v178, v151
	s_and_b64 vcc, vcc, s[0:1]
	v_add_u32_e32 v178, 32, v128
	v_cndmask_b32_e32 v63, v172, v63, vcc
; DI float shx(float v, int m) { return __shfl_xor(v, m, 64); }
; template <int DQK, bool MASKED, int MODE, class MF>
; DI void attn_step(const bf16_t* sK, const bf16_t* sVt, const bf16x8 (&qf)[DQK / 16], f32x16& o0, f32x16& o1, float& m, float& l,
;                   float sc, const MF& mf, int lane, f32x16 (&s)[2], float invl, bool lanevalid = true) {
;     ...
;   float mxr = -3.0e38f;
; #pragma unroll
;   for (int sub = 0; sub < 2; ++sub)
; #pragma unroll
;     for (int q = 0; q < 16; ++q) {
;       if (MASKED) { const int kk = sub * 32 + 16 * (q >> 3) + 8 * h + (q & 7); s[sub][q] = mf(kk) ? s[sub][q] : -3.0e38f; }
;       if (MODE != 2) mxr = fmaxf(mxr, s[sub][q]);
;     }
;   float alpha = 1.f;
;   if (MODE != 2) {
;     float mx = fmaxf(m, mxr * sc);
;     mx = fmaxf(mx, shx(mx, 32));
	v_cmp_le_u32_e32 vcc, v178, v150
	v_cmp_gt_i32_e64 s[0:1], v178, v151
	s_and_b64 vcc, vcc, s[0:1]
	v_cndmask_b32_e32 v178, v172, v32, vcc
	v_add_u32_e32 v32, 33, v128
	v_cmp_le_u32_e32 vcc, v32, v150
	v_cmp_gt_i32_e64 s[0:1], v32, v151
	s_and_b64 vcc, vcc, s[0:1]
	v_add_u32_e32 v32, 34, v128
	v_cndmask_b32_e32 v33, v172, v33, vcc
	v_cmp_le_u32_e32 vcc, v32, v150
	v_cmp_gt_i32_e64 s[0:1], v32, v151
	s_and_b64 vcc, vcc, s[0:1]
	v_add_u32_e32 v32, 35, v128
	v_cndmask_b32_e32 v34, v172, v34, vcc
	v_cmp_le_u32_e32 vcc, v32, v150
	v_cmp_gt_i32_e64 s[0:1], v32, v151
	s_and_b64 vcc, vcc, s[0:1]
	v_add_u32_e32 v32, 36, v128
	v_cndmask_b32_e32 v35, v172, v35, vcc
	v_cmp_le_u32_e32 vcc, v32, v150
	v_cmp_gt_i32_e64 s[0:1], v32, v151
	s_and_b64 vcc, vcc, s[0:1]
	v_add_u32_e32 v32, 37, v128
	v_cndmask_b32_e32 v36, v172, v36, vcc
	v_cmp_le_u32_e32 vcc, v32, v150
	v_cmp_gt_i32_e64 s[0:1], v32, v151
	s_and_b64 vcc, vcc, s[0:1]
	v_add_u32_e32 v32, 38, v128
	v_cndmask_b32_e32 v37, v172, v37, vcc
	v_cmp_le_u32_e32 vcc, v32, v150
	v_cmp_gt_i32_e64 s[0:1], v32, v151
	s_and_b64 vcc, vcc, s[0:1]
	v_or_b32_e32 v32, 39, v177
	v_cndmask_b32_e32 v38, v172, v38, vcc
	v_cmp_le_u32_e32 vcc, v32, v150
	v_cmp_gt_i32_e64 s[0:1], v32, v151
	s_and_b64 vcc, vcc, s[0:1]
	v_add_u32_e32 v32, 48, v128
	v_cndmask_b32_e32 v39, v172, v39, vcc
	v_cmp_le_u32_e32 vcc, v32, v150
	v_cmp_gt_i32_e64 s[0:1], v32, v151
	s_and_b64 vcc, vcc, s[0:1]
	v_add_u32_e32 v32, 49, v128
	v_cndmask_b32_e32 v179, v172, v40, vcc
	v_cmp_le_u32_e32 vcc, v32, v150
	v_cmp_gt_i32_e64 s[0:1], v32, v151
	s_and_b64 vcc, vcc, s[0:1]
	v_add_u32_e32 v32, 50, v128
	v_cndmask_b32_e32 v41, v172, v41, vcc
	v_cmp_le_u32_e32 vcc, v32, v150
	v_cmp_gt_i32_e64 s[0:1], v32, v151
	s_and_b64 vcc, vcc, s[0:1]
	v_add_u32_e32 v32, 51, v128
	v_cndmask_b32_e32 v42, v172, v42, vcc
	v_cmp_le_u32_e32 vcc, v32, v150
	v_cmp_gt_i32_e64 s[0:1], v32, v151
	s_and_b64 vcc, vcc, s[0:1]
	v_add_u32_e32 v32, 52, v128
	v_cndmask_b32_e32 v43, v172, v43, vcc
	v_cmp_le_u32_e32 vcc, v32, v150
	v_cmp_gt_i32_e64 s[0:1], v32, v151
	s_and_b64 vcc, vcc, s[0:1]
	v_add_u32_e32 v32, 53, v128
	v_cndmask_b32_e32 v44, v172, v44, vcc
	v_cmp_le_u32_e32 vcc, v32, v150
	v_cmp_gt_i32_e64 s[0:1], v32, v151
	s_and_b64 vcc, vcc, s[0:1]
	v_add_u32_e32 v32, 54, v128
	v_cndmask_b32_e32 v45, v172, v45, vcc
	v_cmp_le_u32_e32 vcc, v32, v150
	v_cmp_gt_i32_e64 s[0:1], v32, v151
	s_and_b64 vcc, vcc, s[0:1]
	v_or_b32_e32 v32, 55, v177
	v_cndmask_b32_e32 v46, v172, v46, vcc
	v_cmp_le_u32_e32 vcc, v32, v150
	v_cmp_gt_i32_e64 s[0:1], v32, v151
	v_max3_f32 v32, v48, s43, v49
	v_max3_f32 v32, v32, v50, v51
	v_max3_f32 v32, v32, v52, v53
	v_max3_f32 v32, v32, v54, v55
	v_max3_f32 v32, v32, v56, v57
	v_max3_f32 v32, v32, v58, v59
	v_max3_f32 v32, v32, v60, v61
	v_max3_f32 v32, v32, v62, v63
	v_max3_f32 v32, v32, v178, v33
	v_max3_f32 v32, v32, v34, v35
	v_max3_f32 v32, v32, v36, v37
	v_max3_f32 v32, v32, v38, v39
	v_max3_f32 v32, v32, v179, v41
	s_and_b64 vcc, vcc, s[0:1]
	v_max3_f32 v32, v32, v42, v43
	v_cndmask_b32_e32 v47, v172, v47, vcc
	v_max3_f32 v32, v32, v44, v45
	v_max3_f32 v32, v32, v46, v47
	v_mul_f32_e32 v32, 0x3e38aa3b, v32
	v_max_f32_e32 v40, v176, v176
	v_max_f32_e32 v32, v40, v32
	ds_bpermute_b32 v40, v174, v32
	s_add_i32 s47, s47, 1
	s_add_i32 s0, s46, s47
	s_add_i32 s38, s38, 64
	s_add_i32 s0, s0, -1
	s_waitcnt lgkmcnt(0)
; #define MFMA(a, b, c) __builtin_amdgcn_mfma_f32_32x32x16_bf16((a), (b), (c), 0, 0, 0)
; DI unsigned pack2(float a, float b) { f32x2_t v = {a, b}; bf16x2_t r = __builtin_convertvector(v, bf16x2_t); return __builtin_bit_cast(unsigned, r); }
; DI float fexp2(float x) { return __builtin_amdgcn_exp2f(x); }
; DI float shx(float v, int m) { return __shfl_xor(v, m, 64); }
; template <int DQK, bool MASKED, int MODE, class MF>
; DI void attn_step(const bf16_t* sK, const bf16_t* sVt, const bf16x8 (&qf)[DQK / 16], f32x16& o0, f32x16& o1, float& m, float& l,
;                   float sc, const MF& mf, int lane, f32x16 (&s)[2], float invl, bool lanevalid = true) {
;     ...
;   float alpha = 1.f;
;   if (MODE != 2) {
;     float mx = fmaxf(m, mxr * sc);
;     mx = fmaxf(mx, shx(mx, 32));
;     if (!MASKED) mx = lanevalid ? mx : m;
;     alpha = fexp2(m - mx);
;     m = mx;
;   }
;   const float moff = (!MASKED && !lanevalid) ? 1.0e30f : m;
;   float ps = 0.f;
; #pragma unroll
;   for (int sub = 0; sub < 2; ++sub)
; #pragma unroll
;     for (int q = 0; q < 16; ++q) {
;       float pv = fexp2(__builtin_fmaf(s[sub][q], sc, -moff));
;       if (MASKED && MODE != 0) pv = (s[sub][q] > -1.0e38f) ? pv : 0.f;
;       if (MODE == 2) pv *= invl;
;       s[sub][q] = pv;
;       ps += pv;
;     }
;   if (MODE != 2) {
;     ps += shx(ps, 32);
;     l = l * alpha + ps;
;   }
;   if (MODE == 1) return;
;   if (MODE == 0) {
; #pragma unroll
;     for (int q = 0; q < 16; ++q) { o0[q] *= alpha; o1[q] *= alpha; }
;   }
; #pragma unroll
;   for (int sub = 0; sub < 2; ++sub)
; #pragma unroll
;     for (int s2 = 0; s2 < 2; ++s2) {
;       union { bf16x8 v; unsigned u[4]; } pb;
; #pragma unroll
;       for (int e = 0; e < 4; ++e) pb.u[e] = pack2(s[sub][8 * s2 + 2 * e], s[sub][8 * s2 + 2 * e + 1]);
;       o0 = MFMA(vf[sub][s2][0], pb.v, o0);
;       o1 = MFMA(vf[sub][s2][1], pb.v, o1);
;     }
	v_max_f32_e32 v40, v40, v40
	v_max_f32_e32 v32, v32, v40
	v_fma_f32 v40, v48, s44, -v32
	v_exp_f32_e32 v48, v40
	v_fma_f32 v49, v49, s44, -v32
	v_exp_f32_e32 v49, v49
	v_fma_f32 v50, v50, s44, -v32
	v_exp_f32_e32 v50, v50
	v_fma_f32 v51, v51, s44, -v32
	v_exp_f32_e32 v51, v51
	v_fma_f32 v52, v52, s44, -v32
	v_add_f32_e32 v128, 0, v48
	v_exp_f32_e32 v52, v52
	v_fma_f32 v53, v53, s44, -v32
	v_add_f32_e32 v128, v49, v128
	v_exp_f32_e32 v53, v53
	v_fma_f32 v54, v54, s44, -v32
	v_add_f32_e32 v128, v50, v128
	v_exp_f32_e32 v54, v54
	v_fma_f32 v55, v55, s44, -v32
	v_add_f32_e32 v128, v51, v128
	v_exp_f32_e32 v55, v55
	v_fma_f32 v56, v56, s44, -v32
	v_add_f32_e32 v128, v52, v128
	v_exp_f32_e32 v56, v56
	v_fma_f32 v57, v57, s44, -v32
	v_add_f32_e32 v128, v53, v128
	v_exp_f32_e32 v57, v57
	v_fma_f32 v58, v58, s44, -v32
	v_add_f32_e32 v128, v54, v128
	v_exp_f32_e32 v58, v58
	v_fma_f32 v59, v59, s44, -v32
	v_add_f32_e32 v128, v55, v128
	v_exp_f32_e32 v59, v59
	v_fma_f32 v60, v60, s44, -v32
	v_add_f32_e32 v128, v56, v128
	v_exp_f32_e32 v60, v60
	v_fma_f32 v61, v61, s44, -v32
	v_add_f32_e32 v128, v57, v128
	v_exp_f32_e32 v61, v61
	v_fma_f32 v62, v62, s44, -v32
	v_add_f32_e32 v128, v58, v128
	v_exp_f32_e32 v62, v62
	v_fma_f32 v63, v63, s44, -v32
	v_sub_f32_e32 v40, v176, v32
	v_add_f32_e32 v128, v59, v128
	v_exp_f32_e32 v63, v63
	v_fma_f32 v176, v178, s44, -v32
	v_add_f32_e32 v128, v60, v128
	v_exp_f32_e32 v176, v176
	v_fma_f32 v33, v33, s44, -v32
	v_add_f32_e32 v128, v61, v128
	v_exp_f32_e32 v33, v33
	v_fma_f32 v34, v34, s44, -v32
	v_add_f32_e32 v128, v62, v128
	v_exp_f32_e32 v177, v34
	v_fma_f32 v34, v35, s44, -v32
	v_add_f32_e32 v128, v63, v128
	v_exp_f32_e32 v178, v34
	v_fma_f32 v34, v36, s44, -v32
	v_add_f32_e32 v128, v176, v128
	v_exp_f32_e32 v180, v34
	v_fma_f32 v35, v37, s44, -v32
	v_add_f32_e32 v34, v33, v128
	v_exp_f32_e32 v128, v35
	v_fma_f32 v35, v38, s44, -v32
	v_add_f32_e32 v34, v177, v34
	v_exp_f32_e32 v38, v35
	v_fma_f32 v35, v39, s44, -v32
	v_add_f32_e32 v34, v178, v34
	v_exp_f32_e32 v39, v35
	v_add_f32_e32 v34, v180, v34
	v_exp_f32_e32 v40, v40
	v_add_f32_e32 v34, v128, v34
	v_add_f32_e32 v34, v38, v34
	v_add_f32_e32 v181, v39, v34
	v_fma_f32 v34, v179, s44, -v32
	v_exp_f32_e32 v179, v34
	v_pk_mul_f32 v[14:15], v[14:15], v[40:41] op_sel_hi:[1,0]
	v_pk_mul_f32 v[12:13], v[12:13], v[40:41] op_sel_hi:[1,0]
	v_pk_mul_f32 v[10:11], v[10:11], v[40:41] op_sel_hi:[1,0]
	v_pk_mul_f32 v[8:9], v[8:9], v[40:41] op_sel_hi:[1,0]
	v_pk_mul_f32 v[6:7], v[6:7], v[40:41] op_sel_hi:[1,0]
	v_pk_mul_f32 v[4:5], v[4:5], v[40:41] op_sel_hi:[1,0]
	v_pk_mul_f32 v[2:3], v[2:3], v[40:41] op_sel_hi:[1,0]
	v_pk_mul_f32 v[0:1], v[0:1], v[40:41] op_sel_hi:[1,0]
	v_pk_mul_f32 v[30:31], v[30:31], v[40:41] op_sel_hi:[1,0]
	v_cvt_pk_bf16_f32 v34, v48, v49
	v_cvt_pk_bf16_f32 v35, v50, v51
	v_cvt_pk_bf16_f32 v36, v52, v53
	v_cvt_pk_bf16_f32 v37, v54, v55
	v_pk_mul_f32 v[28:29], v[28:29], v[40:41] op_sel_hi:[1,0]
	v_pk_mul_f32 v[26:27], v[26:27], v[40:41] op_sel_hi:[1,0]
	v_pk_mul_f32 v[24:25], v[24:25], v[40:41] op_sel_hi:[1,0]
	v_pk_mul_f32 v[22:23], v[22:23], v[40:41] op_sel_hi:[1,0]
	v_pk_mul_f32 v[20:21], v[20:21], v[40:41] op_sel_hi:[1,0]
	v_pk_mul_f32 v[18:19], v[18:19], v[40:41] op_sel_hi:[1,0]
	v_pk_mul_f32 v[16:17], v[16:17], v[40:41] op_sel_hi:[1,0]
	v_mfma_f32_32x32x16_bf16 v[0:15], v[124:127], v[34:37], v[0:15]
	v_fma_f32 v42, v42, s44, -v32
	v_exp_f32_e32 v42, v42
	v_fma_f32 v43, v43, s44, -v32
	v_exp_f32_e32 v43, v43
	v_fma_f32 v44, v44, s44, -v32
	v_add_f32_e32 v48, v179, v181
	v_exp_f32_e32 v44, v44
	v_mfma_f32_32x32x16_bf16 v[16:31], v[120:123], v[34:37], v[16:31]
	v_fma_f32 v34, v41, s44, -v32
	v_exp_f32_e32 v41, v34
	v_cvt_pk_bf16_f32 v34, v56, v57
	v_cvt_pk_bf16_f32 v35, v58, v59
	v_cvt_pk_bf16_f32 v36, v60, v61
	v_cvt_pk_bf16_f32 v37, v62, v63
	v_add_f32_e32 v48, v41, v48
	s_cmp_ge_u32 s0, s41
	v_mfma_f32_32x32x16_bf16 v[0:15], v[116:119], v[34:37], v[0:15]
	v_mfma_f32_32x32x16_bf16 v[16:31], v[112:115], v[34:37], v[16:31]
	v_add_f32_e32 v34, v42, v48
	v_add_f32_e32 v34, v43, v34
	v_add_f32_e32 v48, v44, v34
	v_cvt_pk_bf16_f32 v34, v176, v33
	v_cvt_pk_bf16_f32 v35, v177, v178
	v_cvt_pk_bf16_f32 v36, v180, v128
	v_cvt_pk_bf16_f32 v37, v38, v39
	v_fma_f32 v33, v45, s44, -v32
	v_fma_f32 v38, v46, s44, -v32
	v_mfma_f32_32x32x16_bf16 v[0:15], v[108:111], v[34:37], v[0:15]
	v_exp_f32_e32 v33, v33
	v_exp_f32_e32 v39, v38
	v_fma_f32 v38, v47, s44, -v32
	v_exp_f32_e32 v45, v38
	v_add_f32_e32 v38, v33, v48
	v_mfma_f32_32x32x16_bf16 v[16:31], v[104:107], v[34:37], v[16:31]
	v_add_f32_e32 v34, v39, v38
	v_cvt_pk_bf16_f32 v36, v179, v41
	v_cvt_pk_bf16_f32 v37, v42, v43
	v_cvt_pk_bf16_f32 v38, v44, v33
	v_cvt_pk_bf16_f32 v39, v39, v45
	v_add_f32_e32 v34, v45, v34
	ds_bpermute_b32 v35, v174, v34
	v_mfma_f32_32x32x16_bf16 v[0:15], v[100:103], v[36:39], v[0:15]
	s_waitcnt lgkmcnt(0)
	v_add_f32_e32 v34, v34, v35
	v_fmac_f32_e32 v34, v175, v40
	v_mfma_f32_32x32x16_bf16 v[16:31], v[96:99], v[36:39], v[16:31]
	s_cbranch_scc1 .LBB0_337
	v_mov_b32_e32 v175, v34
	v_mov_b32_e32 v176, v32
	s_branch .LBB0_346

; #define MFMA(a, b, c) __builtin_amdgcn_mfma_f32_32x32x16_bf16((a), (b), (c), 0, 0, 0)
; template <int DQK, bool MASKED, int MODE, class MF>
; DI void attn_step(const bf16_t* sK, const bf16_t* sVt, const bf16x8 (&qf)[DQK / 16], f32x16& o0, f32x16& o1, float& m, float& l,
;                   float sc, const MF& mf, int lane, f32x16 (&s)[2], float invl, bool lanevalid = true) {
;     ...
;   bf16x8 kf[2][DQK / 16];
; #pragma unroll
;   for (int sub = 0; sub < 2; ++sub)
; #pragma unroll
;     for (int ks = 0; ks < DQK / 16; ++ks) kf[sub][ks] = *(const bf16x8*)(sK + (sub * 32 + pr) * KST + ks * 16 + 8 * h);
;   __builtin_amdgcn_sched_barrier(0);
; #pragma unroll
;   for (int q = 0; q < 16; ++q) { s[0][q] = 0.f; s[1][q] = 0.f; }
; #pragma unroll
;   for (int ks = 0; ks < DQK / 16; ++ks) {
;     s[0] = MFMA(kf[0][ks], qf[ks], s[0]);
;     s[1] = MFMA(kf[1][ks], qf[ks], s[1]);
;   }
; DI void phase_attn_nsa(const Params& P, bf16_t* og, unsigned char* smem, int L, int G) {
;     ...
;       for (int j = 0; j <= jhi; ++j) {
;         const int key0 = j * 64, cb = j & 1;
;         __syncthreads();
;         if (j < jhi) kv64_store(R, sK + (cb ^ 1) * KVB64, sVt + (cb ^ 1) * KVB64, tid);
;         if (j + 1 < jhi) kv64_fetch(R, kb, 256, vb, SEQ, key0 + 128, true, tid);
;         __builtin_amdgcn_sched_barrier(0);
;         if ((selU >> j) & 1u) {
;           const bool lsel = (sel >> j) & 1u;
;           auto mf = [&](int kk) { return lsel && (key0 + kk <= t); };
;           if (key0 + 63 > t0) attn_step<64, true, 0>(sK + cb * KVB64, sVt + cb * KVB64, qf, o0, o1, m, l, sc, mf, lane, s, 0.f);
;           else attn_step<64, false, 0>(sK + cb * KVB64, sVt + cb * KVB64, qf, o0, o1, m, l, sc, mf, lane, s, 0.f, lsel);
.LBB0_1345:
	s_and_b32 s5, s0, 1
	s_cmp_ge_u32 s0, s20
	s_cselect_b32 s99, 0, 1
	s_add_i32 s4, s0, 1
	s_cmp_ge_u32 s4, s20
	s_cselect_b32 s98, 0, 2
	s_or_b32 s99, s99, s98
	s_xor_b32 s98, s5, 1
	s_mulk_i32 s98, 0x4800
	s_waitcnt lgkmcnt(0)
	s_barrier
.LBB0_1347:
.LBB0_1349:
	s_lshr_b32 s1, s2, s0
	s_bitcmp0_b32 s1, 0
	s_cbranch_scc1 .Lmy_hm1345_skip
	v_lshrrev_b32_e32 v0, s0, v183
	s_add_i32 s6, s44, 63
	s_mulk_i32 s5, 0x4800
	v_and_b32_e32 v190, 1, v0
	s_mov_b64 s[0:1], -1
	s_cmp_le_u32 s6, s46
	v_max_f32_e32 v188, v141, v141
	v_add_u32_e32 v189, s5, v153
	v_cmp_eq_u32_e32 vcc, 1, v190
	s_cbranch_scc0 .LBB0_1352
	v_add_u32_e32 v0, s5, v182
	ds_read_b128 v[34:37], v0
	ds_read_b128 v[38:41], v0 offset:32
	ds_read_b128 v[106:109], v0 offset:64
	ds_read_b128 v[110:113], v0 offset:96
	ds_read_b128 v[42:45], v0 offset:4608
	ds_read_b128 v[114:117], v0 offset:4640
	ds_read_b128 v[118:121], v0 offset:4672
	ds_read_b128 v[194:197], v0 offset:4704
	s_waitcnt lgkmcnt(7)
	v_mfma_f32_32x32x16_bf16 v[58:73], v[34:37], v[74:77], 0
	v_add3_u32 v0, v189, v175, v138
	v_add3_u32 v34, v189, v177, v138
	s_waitcnt lgkmcnt(3)
	v_mfma_f32_32x32x16_bf16 v[42:57], v[42:45], v[74:77], 0
	v_mfma_f32_32x32x16_bf16 v[58:73], v[38:41], v[78:81], v[58:73]
	s_bitcmp1_b32 s99, 0
	s_cbranch_scc0 .Lmy_hm1345_0_ns
	v_add_u32_e32 v247, s98, v170
	s_waitcnt vmcnt(3)
	ds_write_b128 v247, v[90:93]
	s_waitcnt vmcnt(2)
	ds_write_b128 v247, v[94:97] offset:4608
	s_waitcnt vmcnt(1)
	ds_write_b128 v247, v[98:101] offset:9216
	s_waitcnt vmcnt(0)
	ds_write_b128 v247, v[102:105] offset:13824
	s_branch .Lmy_hm1345_0_sd
.Lmy_hm1345_0_ns:
	ds_read_b32 v247, v170
	ds_read_b32 v247, v170
	ds_read_b32 v247, v170
	ds_read_b32 v247, v170
.Lmy_hm1345_0_sd:
	s_bitcmp1_b32 s99, 1
	s_cbranch_scc0 .Lmy_hm1345_0_np
	v_mov_b32_e32 v249, 0
	v_add_u32_e32 v252, s44, v169
	v_add_u32_e32 v248, 0x80, v252
	v_lshlrev_b64 v[250:251], 9, v[248:249]
	v_add_u32_e32 v248, 0xa0, v252
	v_lshl_add_u64 v[250:251], v[150:151], 0, v[250:251]
	v_lshlrev_b64 v[252:253], 9, v[248:249]
	s_lshl_b64 s[100:101], s[44:45], 1
	v_lshl_add_u64 v[252:253], v[150:151], 0, v[252:253]
	global_load_dwordx4 v[90:93], v[250:251], off
	global_load_dwordx4 v[94:97], v[252:253], off
	v_lshl_add_u64 v[250:251], v[146:147], 0, s[100:101]
	v_lshl_add_u64 v[252:253], v[148:149], 0, s[100:101]
	global_load_dwordx4 v[98:101], v[250:251], off offset:256
	global_load_dwordx4 v[102:105], v[252:253], off offset:256
.Lmy_hm1345_0_np:
	s_waitcnt lgkmcnt(6)
	v_mfma_f32_32x32x16_bf16 v[42:57], v[114:117], v[78:81], v[42:57]
	v_mfma_f32_32x32x16_bf16 v[58:73], v[106:109], v[82:85], v[58:73]
	s_waitcnt lgkmcnt(5)
	v_mfma_f32_32x32x16_bf16 v[42:57], v[118:121], v[82:85], v[42:57]
	v_mfma_f32_32x32x16_bf16 v[58:73], v[110:113], v[86:89], v[58:73]
	ds_read_b128 v[198:201], v0 offset:9216
	ds_read_b128 v[126:129], v0 offset:9248
	ds_read_b128 v[130:133], v34 offset:9216
	ds_read_b128 v[122:125], v34 offset:9248
	ds_read_b128 v[118:121], v0 offset:9280
	ds_read_b128 v[110:113], v0 offset:9312
	ds_read_b128 v[114:117], v34 offset:9280
	ds_read_b128 v[106:109], v34 offset:9312
	s_waitcnt lgkmcnt(12)
	v_mfma_f32_32x32x16_bf16 v[42:57], v[194:197], v[86:89], v[42:57]
	s_nop 1
	v_max3_f32 v0, v58, s8, v59
	v_max3_f32 v0, v0, v60, v61
	v_max3_f32 v0, v0, v62, v63
	v_max3_f32 v0, v0, v64, v65
	v_max3_f32 v0, v0, v66, v67
	v_max3_f32 v0, v0, v68, v69
	v_max3_f32 v0, v0, v70, v71
	v_max3_f32 v0, v0, v72, v73
	s_nop 1
	v_max3_f32 v0, v0, v42, v43
	v_max3_f32 v0, v0, v44, v45
	v_max3_f32 v0, v0, v46, v47
	v_max3_f32 v0, v0, v48, v49
	v_max3_f32 v0, v0, v50, v51
	v_max3_f32 v0, v0, v52, v53
	v_max3_f32 v0, v0, v54, v55
	v_max3_f32 v0, v0, v56, v57
	v_mul_f32_e32 v0, 0x3e38aa3b, v0
	v_max_f32_e32 v0, v188, v0
	ds_bpermute_b32 v34, v173, v0
	s_mov_b64 s[0:1], 0
	s_waitcnt lgkmcnt(0)
; #define MFMA(a, b, c) __builtin_amdgcn_mfma_f32_32x32x16_bf16((a), (b), (c), 0, 0, 0)
; DI unsigned pack2(float a, float b) { f32x2_t v = {a, b}; bf16x2_t r = __builtin_convertvector(v, bf16x2_t); return __builtin_bit_cast(unsigned, r); }
; DI float fexp2(float x) { return __builtin_amdgcn_exp2f(x); }
; DI float shx(float v, int m) { return __shfl_xor(v, m, 64); }
; template <int DQK, bool MASKED, int MODE, class MF>
; DI void attn_step(const bf16_t* sK, const bf16_t* sVt, const bf16x8 (&qf)[DQK / 16], f32x16& o0, f32x16& o1, float& m, float& l,
;                   float sc, const MF& mf, int lane, f32x16 (&s)[2], float invl, bool lanevalid = true) {
;     ...
;   bf16x8 kf[2][DQK / 16];
; #pragma unroll
;   for (int sub = 0; sub < 2; ++sub)
; #pragma unroll
;     for (int ks = 0; ks < DQK / 16; ++ks) kf[sub][ks] = *(const bf16x8*)(sK + (sub * 32 + pr) * KST + ks * 16 + 8 * h);
;   __builtin_amdgcn_sched_barrier(0);
; #pragma unroll
;   for (int q = 0; q < 16; ++q) { s[0][q] = 0.f; s[1][q] = 0.f; }
; #pragma unroll
;   for (int ks = 0; ks < DQK / 16; ++ks) {
;     s[0] = MFMA(kf[0][ks], qf[ks], s[0]);
;     s[1] = MFMA(kf[1][ks], qf[ks], s[1]);
;   }
;     ...
;   float alpha = 1.f;
;   if (MODE != 2) {
;     float mx = fmaxf(m, mxr * sc);
;     mx = fmaxf(mx, shx(mx, 32));
;     if (!MASKED) mx = lanevalid ? mx : m;
;     alpha = fexp2(m - mx);
;     m = mx;
;   }
;   const float moff = (!MASKED && !lanevalid) ? 1.0e30f : m;
;   float ps = 0.f;
; #pragma unroll
;   for (int sub = 0; sub < 2; ++sub)
; #pragma unroll
;     for (int q = 0; q < 16; ++q) {
;       float pv = fexp2(__builtin_fmaf(s[sub][q], sc, -moff));
;       if (MASKED && MODE != 0) pv = (s[sub][q] > -1.0e38f) ? pv : 0.f;
;       if (MODE == 2) pv *= invl;
;       s[sub][q] = pv;
;       ps += pv;
;     }
;   if (MODE != 2) {
;     ps += shx(ps, 32);
;     l = l * alpha + ps;
;   }
;   if (MODE == 1) return;
;   if (MODE == 0) {
; #pragma unroll
;     for (int q = 0; q < 16; ++q) { o0[q] *= alpha; o1[q] *= alpha; }
;   }
; #pragma unroll
;   for (int sub = 0; sub < 2; ++sub)
; #pragma unroll
;     for (int s2 = 0; s2 < 2; ++s2) {
;       union { bf16x8 v; unsigned u[4]; } pb;
; #pragma unroll
;       for (int e = 0; e < 4; ++e) pb.u[e] = pack2(s[sub][8 * s2 + 2 * e], s[sub][8 * s2 + 2 * e + 1]);
;       o0 = MFMA(vf[sub][s2][0], pb.v, o0);
;       o1 = MFMA(vf[sub][s2][1], pb.v, o1);
;     }
	v_max_f32_e32 v34, v34, v34
	v_max_f32_e32 v34, v0, v34
	v_cndmask_b32_e64 v191, v167, -v34, vcc
	v_fmamk_f32 v35, v58, 0x3e38aa3b, v191
	v_fmamk_f32 v36, v59, 0x3e38aa3b, v191
	v_exp_f32_e32 v58, v35
	v_fmamk_f32 v37, v60, 0x3e38aa3b, v191
	v_exp_f32_e32 v59, v36
	v_exp_f32_e32 v60, v37
	v_fmamk_f32 v35, v61, 0x3e38aa3b, v191
	v_exp_f32_e32 v61, v35
	v_add_f32_e32 v36, 0, v58
	v_fmamk_f32 v35, v62, 0x3e38aa3b, v191
	v_add_f32_e32 v36, v59, v36
	v_exp_f32_e32 v62, v35
	v_fmamk_f32 v35, v63, 0x3e38aa3b, v191
	v_add_f32_e32 v36, v60, v36
	v_exp_f32_e32 v63, v35
	v_fmamk_f32 v35, v64, 0x3e38aa3b, v191
	v_exp_f32_e32 v64, v35
	v_add_f32_e32 v35, v61, v36
	v_fmamk_f32 v36, v65, 0x3e38aa3b, v191
	v_exp_f32_e32 v65, v36
	v_fmamk_f32 v36, v66, 0x3e38aa3b, v191
	v_add_f32_e32 v35, v62, v35
	v_exp_f32_e32 v203, v36
	v_fmamk_f32 v36, v67, 0x3e38aa3b, v191
	v_add_f32_e32 v35, v63, v35
	v_exp_f32_e32 v204, v36
	v_fmamk_f32 v36, v68, 0x3e38aa3b, v191
	v_add_f32_e32 v35, v64, v35
	v_exp_f32_e32 v205, v36
	v_fmamk_f32 v36, v69, 0x3e38aa3b, v191
	v_add_f32_e32 v35, v65, v35
	v_exp_f32_e32 v206, v36
	v_fmamk_f32 v36, v70, 0x3e38aa3b, v191
	v_add_f32_e32 v35, v203, v35
	v_exp_f32_e32 v207, v36
	v_fmamk_f32 v36, v71, 0x3e38aa3b, v191
	v_add_f32_e32 v35, v204, v35
	v_exp_f32_e32 v208, v36
	v_fmamk_f32 v36, v72, 0x3e38aa3b, v191
	v_add_f32_e32 v35, v205, v35
	v_exp_f32_e32 v209, v36
	v_fmamk_f32 v36, v73, 0x3e38aa3b, v191
	v_add_f32_e32 v35, v206, v35
	v_exp_f32_e32 v210, v36
	v_fmamk_f32 v36, v42, 0x3e38aa3b, v191
	v_add_f32_e32 v35, v207, v35
	v_exp_f32_e32 v211, v36
	v_fmamk_f32 v36, v43, 0x3e38aa3b, v191
	v_add_f32_e32 v35, v208, v35
	v_exp_f32_e32 v212, v36
	v_fmamk_f32 v36, v44, 0x3e38aa3b, v191
	v_add_f32_e32 v35, v209, v35
	v_exp_f32_e32 v213, v36
	v_fmamk_f32 v36, v45, 0x3e38aa3b, v191
	v_add_f32_e32 v35, v210, v35
	v_exp_f32_e32 v214, v36
	v_fmamk_f32 v36, v46, 0x3e38aa3b, v191
	v_add_f32_e32 v35, v211, v35
	v_exp_f32_e32 v215, v36
	v_fmamk_f32 v36, v47, 0x3e38aa3b, v191
	v_cndmask_b32_e32 v0, v141, v34, vcc
	v_add_f32_e32 v35, v212, v35
	v_exp_f32_e32 v216, v36
	v_fmamk_f32 v36, v48, 0x3e38aa3b, v191
	v_sub_f32_e32 v34, v141, v0
	v_add_f32_e32 v35, v213, v35
	v_exp_f32_e32 v217, v36
	v_add_f32_e32 v35, v214, v35
	v_exp_f32_e32 v202, v34
	v_add_f32_e32 v35, v215, v35
	v_add_f32_e32 v35, v216, v35
	v_add_f32_e32 v218, v217, v35
	v_fmamk_f32 v35, v49, 0x3e38aa3b, v191
	v_fmamk_f32 v34, v50, 0x3e38aa3b, v191
	v_exp_f32_e32 v219, v35
	v_exp_f32_e32 v220, v34
	v_pk_mul_f32 v[32:33], v[32:33], v[202:203] op_sel_hi:[1,0]
	v_pk_mul_f32 v[30:31], v[30:31], v[202:203] op_sel_hi:[1,0]
	v_pk_mul_f32 v[28:29], v[28:29], v[202:203] op_sel_hi:[1,0]
	v_pk_mul_f32 v[26:27], v[26:27], v[202:203] op_sel_hi:[1,0]
	v_pk_mul_f32 v[24:25], v[24:25], v[202:203] op_sel_hi:[1,0]
	v_pk_mul_f32 v[22:23], v[22:23], v[202:203] op_sel_hi:[1,0]
	v_pk_mul_f32 v[20:21], v[20:21], v[202:203] op_sel_hi:[1,0]
	v_pk_mul_f32 v[18:19], v[18:19], v[202:203] op_sel_hi:[1,0]
	v_cvt_pk_bf16_f32 v194, v58, v59
	v_cvt_pk_bf16_f32 v195, v60, v61
	v_cvt_pk_bf16_f32 v196, v62, v63
	v_cvt_pk_bf16_f32 v197, v64, v65
	v_pk_mul_f32 v[16:17], v[16:17], v[202:203] op_sel_hi:[1,0]
	v_pk_mul_f32 v[14:15], v[14:15], v[202:203] op_sel_hi:[1,0]
	v_mfma_f32_32x32x16_bf16 v[18:33], v[198:201], v[194:197], v[18:33]
	v_mul_f32_e64 v12, v12, v202
	v_mul_f32_e64 v13, v13, v202
	v_mul_f32_e64 v10, v10, v202
	v_mul_f32_e64 v11, v11, v202
	v_mul_f32_e64 v8, v8, v202
	v_mul_f32_e64 v9, v9, v202
	v_pk_mul_f32 v[6:7], v[6:7], v[202:203] op_sel_hi:[1,0]
	v_pk_mul_f32 v[4:5], v[4:5], v[202:203] op_sel_hi:[1,0]
	v_pk_mul_f32 v[2:3], v[2:3], v[202:203] op_sel_hi:[1,0]
	v_fmamk_f32 v51, v51, 0x3e38aa3b, v191
	v_add_f32_e32 v50, v219, v218
	v_mfma_f32_32x32x16_bf16 v[2:17], v[130:133], v[194:197], v[2:17]
	v_cvt_pk_bf16_f32 v130, v203, v204
	v_cvt_pk_bf16_f32 v131, v205, v206
	v_cvt_pk_bf16_f32 v132, v207, v208
	v_cvt_pk_bf16_f32 v133, v209, v210
	v_add_f32_e32 v50, v220, v50
	v_fmamk_f32 v55, v55, 0x3e38aa3b, v191
	v_exp_f32_e32 v55, v55
	v_mfma_f32_32x32x16_bf16 v[18:33], v[126:129], v[130:133], v[18:33]
	v_exp_f32_e32 v126, v51
	v_fmamk_f32 v51, v52, 0x3e38aa3b, v191
	v_exp_f32_e32 v127, v51
	v_fmamk_f32 v51, v53, 0x3e38aa3b, v191
	v_exp_f32_e32 v128, v51
	v_add_f32_e32 v50, v126, v50
	v_add_f32_e32 v50, v127, v50
	v_mfma_f32_32x32x16_bf16 v[2:17], v[122:125], v[130:133], v[2:17]
	v_add_f32_e32 v122, v128, v50
	v_fmamk_f32 v50, v54, 0x3e38aa3b, v191
	v_exp_f32_e32 v54, v50
	v_fmamk_f32 v56, v56, 0x3e38aa3b, v191
	v_exp_f32_e32 v56, v56
	v_fmac_f32_e32 v191, 0x3e38aa3b, v57
	v_cvt_pk_bf16_f32 v50, v211, v212
	v_cvt_pk_bf16_f32 v51, v213, v214
	v_cvt_pk_bf16_f32 v52, v215, v216
	v_cvt_pk_bf16_f32 v53, v217, v219
	v_exp_f32_e32 v57, v191
	s_nop 0
	v_mfma_f32_32x32x16_bf16 v[18:33], v[118:121], v[50:53], v[18:33]
	v_add_f32_e32 v118, v54, v122
	v_cvt_pk_bf16_f32 v54, v54, v55
	v_mfma_f32_32x32x16_bf16 v[2:17], v[114:117], v[50:53], v[2:17]
	v_add_f32_e32 v50, v55, v118
	v_add_f32_e32 v50, v56, v50
	v_add_f32_e32 v50, v57, v50
	v_cvt_pk_bf16_f32 v52, v220, v126
	v_cvt_pk_bf16_f32 v53, v127, v128
	v_cvt_pk_bf16_f32 v55, v56, v57
	s_nop 1
	v_mfma_f32_32x32x16_bf16 v[18:33], v[110:113], v[52:55], v[18:33]
	v_mfma_f32_32x32x16_bf16 v[2:17], v[106:109], v[52:55], v[2:17]
	v_fma_f32 v50, v185, v202, v50
	s_nop 11
	v_mov_b32_e32 v141, v0
	v_mov_b32_e32 v185, v50
	s_branch .LBB0_1355
.LBB0_1352:
	s_andn2_b64 vcc, exec, s[0:1]
	s_cbranch_vccnz .LBB0_1354
	v_add_u32_e32 v0, s5, v172
	s_nop 6
	ds_read_b128 v[34:37], v0
	s_nop 0
	ds_read_b128 v[66:69], v0 offset:32
	ds_read_b128 v[70:73], v0 offset:64
	ds_read_b128 v[106:109], v0 offset:96
	ds_read_b128 v[38:41], v0 offset:4608
	ds_read_b128 v[110:113], v0 offset:4640
	ds_read_b128 v[114:117], v0 offset:4672
	ds_read_b128 v[194:197], v0 offset:4704
	v_cmp_eq_u32_e32 vcc, 1, v190
	s_waitcnt lgkmcnt(7)
	v_mfma_f32_32x32x16_bf16 v[50:65], v[34:37], v[74:77], 0
	v_lshlrev_b32_e32 v0, 1, v171
	s_waitcnt lgkmcnt(3)
	v_mfma_f32_32x32x16_bf16 v[34:49], v[38:41], v[74:77], 0
	v_mfma_f32_32x32x16_bf16 v[50:65], v[66:69], v[78:81], v[50:65]
	s_bitcmp1_b32 s99, 0
	s_cbranch_scc0 .Lmy_hm1345_1_ns
	v_add_u32_e32 v247, s98, v170
	s_waitcnt vmcnt(3)
	ds_write_b128 v247, v[90:93]
	s_waitcnt vmcnt(2)
	ds_write_b128 v247, v[94:97] offset:4608
	s_waitcnt vmcnt(1)
	ds_write_b128 v247, v[98:101] offset:9216
	s_waitcnt vmcnt(0)
	ds_write_b128 v247, v[102:105] offset:13824
	s_branch .Lmy_hm1345_1_sd

; DI float fexp2(float x) { return __builtin_amdgcn_exp2f(x); }
; DI float shx(float v, int m) { return __shfl_xor(v, m, 64); }
; template <int DQK, bool MASKED, int MODE, class MF>
; DI void attn_step(const bf16_t* sK, const bf16_t* sVt, const bf16x8 (&qf)[DQK / 16], f32x16& o0, f32x16& o1, float& m, float& l,
;                   float sc, const MF& mf, int lane, f32x16 (&s)[2], float invl, bool lanevalid = true) {
;     ...
;   bf16x8 vf[2][2][2];
;   if (MODE != 1) {
; #pragma unroll
;     for (int sub = 0; sub < 2; ++sub)
; #pragma unroll
;       for (int s2 = 0; s2 < 2; ++s2) {
;         vf[sub][s2][0] = *(const bf16x8*)(sVt + r * 72 + sub * 32 + s2 * 16 + 8 * h);
;         vf[sub][s2][1] = *(const bf16x8*)(sVt + (32 + r) * 72 + sub * 32 + s2 * 16 + 8 * h);
;       }
;     __builtin_amdgcn_sched_barrier(0);
;   }
;   float mxr = -3.0e38f;
; #pragma unroll
;   for (int sub = 0; sub < 2; ++sub)
; #pragma unroll
;     for (int q = 0; q < 16; ++q) {
;       if (MASKED) { const int kk = sub * 32 + 16 * (q >> 3) + 8 * h + (q & 7); s[sub][q] = mf(kk) ? s[sub][q] : -3.0e38f; }
;       if (MODE != 2) mxr = fmaxf(mxr, s[sub][q]);
;     }
;   float alpha = 1.f;
;   if (MODE != 2) {
;     float mx = fmaxf(m, mxr * sc);
;     mx = fmaxf(mx, shx(mx, 32));
;     if (!MASKED) mx = lanevalid ? mx : m;
;     alpha = fexp2(m - mx);
;     m = mx;
;   }
.Lmy_hm1345_1_np:
	s_waitcnt lgkmcnt(6)
	v_mfma_f32_32x32x16_bf16 v[34:49], v[110:113], v[78:81], v[34:49]
	v_mfma_f32_32x32x16_bf16 v[50:65], v[70:73], v[82:85], v[50:65]
	v_add3_u32 v70, v189, v175, v0
	v_add3_u32 v0, v189, v177, v0
	s_waitcnt lgkmcnt(5)
	v_mfma_f32_32x32x16_bf16 v[34:49], v[114:117], v[82:85], v[34:49]
	v_mfma_f32_32x32x16_bf16 v[50:65], v[106:109], v[86:89], v[50:65]
	ds_read_b128 v[66:69], v70 offset:9216
	ds_read_b128 v[126:129], v70 offset:9248
	ds_read_b128 v[130:133], v0 offset:9216
	ds_read_b128 v[122:125], v0 offset:9248
	ds_read_b128 v[118:121], v70 offset:9280
	ds_read_b128 v[110:113], v70 offset:9312
	ds_read_b128 v[114:117], v0 offset:9280
	ds_read_b128 v[106:109], v0 offset:9312
	s_waitcnt lgkmcnt(12)
	v_mfma_f32_32x32x16_bf16 v[34:49], v[194:197], v[86:89], v[34:49]
	v_add_u32_e32 v0, s44, v171
	v_cmp_le_u32_e64 s[0:1], v0, v136
	s_and_b64 s[0:1], vcc, s[0:1]
	v_add_u32_e32 v70, 2, v0
	v_cndmask_b32_e64 v50, v166, v50, s[0:1]
	v_cmp_lt_u32_e64 s[0:1], v0, v136
	s_and_b64 s[0:1], vcc, s[0:1]
	s_nop 0
	v_cndmask_b32_e64 v51, v166, v51, s[0:1]
	v_cmp_le_u32_e64 s[0:1], v70, v136
	s_and_b64 s[0:1], vcc, s[0:1]
	v_add_u32_e32 v70, 3, v0
	v_cndmask_b32_e64 v52, v166, v52, s[0:1]
	v_cmp_le_u32_e64 s[0:1], v70, v136
	s_and_b64 s[0:1], vcc, s[0:1]
	v_add_u32_e32 v70, 4, v0
	v_cndmask_b32_e64 v53, v166, v53, s[0:1]
	v_cmp_le_u32_e64 s[0:1], v70, v136
	s_and_b64 s[0:1], vcc, s[0:1]
	v_add_u32_e32 v70, 5, v0
	v_cndmask_b32_e64 v54, v166, v54, s[0:1]
	v_cmp_le_u32_e64 s[0:1], v70, v136
	s_and_b64 s[0:1], vcc, s[0:1]
	v_add_u32_e32 v70, 6, v0
	v_cndmask_b32_e64 v55, v166, v55, s[0:1]
	v_cmp_le_u32_e64 s[0:1], v70, v136
	v_add_u32_e32 v70, s44, v139
	s_and_b64 s[0:1], vcc, s[0:1]
	v_or_b32_e32 v71, 7, v70
	v_cndmask_b32_e64 v56, v166, v56, s[0:1]
	v_cmp_le_u32_e64 s[0:1], v71, v136
	s_and_b64 s[0:1], vcc, s[0:1]
	v_add_u32_e32 v71, 16, v0
	v_cndmask_b32_e64 v57, v166, v57, s[0:1]
	v_cmp_le_u32_e64 s[0:1], v71, v136
	s_and_b64 s[0:1], vcc, s[0:1]
	v_add_u32_e32 v71, 17, v0
	v_cndmask_b32_e64 v58, v166, v58, s[0:1]
	v_cmp_le_u32_e64 s[0:1], v71, v136
	s_and_b64 s[0:1], vcc, s[0:1]
	v_add_u32_e32 v71, 18, v0
	v_cndmask_b32_e64 v59, v166, v59, s[0:1]
	v_cmp_le_u32_e64 s[0:1], v71, v136
	s_and_b64 s[0:1], vcc, s[0:1]
	v_add_u32_e32 v71, 19, v0
	v_cndmask_b32_e64 v60, v166, v60, s[0:1]
	v_cmp_le_u32_e64 s[0:1], v71, v136
	s_and_b64 s[0:1], vcc, s[0:1]
	v_add_u32_e32 v71, 20, v0
	v_cndmask_b32_e64 v61, v166, v61, s[0:1]
	v_cmp_le_u32_e64 s[0:1], v71, v136
	s_and_b64 s[0:1], vcc, s[0:1]
	v_add_u32_e32 v71, 21, v0
	v_cndmask_b32_e64 v62, v166, v62, s[0:1]
	v_cmp_le_u32_e64 s[0:1], v71, v136
	s_and_b64 s[0:1], vcc, s[0:1]
	v_add_u32_e32 v71, 22, v0
	v_cndmask_b32_e64 v63, v166, v63, s[0:1]
	v_cmp_le_u32_e64 s[0:1], v71, v136
	s_and_b64 s[0:1], vcc, s[0:1]
	v_or_b32_e32 v71, 23, v70
	v_cndmask_b32_e64 v64, v166, v64, s[0:1]
	v_cmp_le_u32_e64 s[0:1], v71, v136
	s_and_b64 s[0:1], vcc, s[0:1]
	v_add_u32_e32 v71, 32, v0
	v_cndmask_b32_e64 v65, v166, v65, s[0:1]
	v_cmp_le_u32_e64 s[0:1], v71, v136
	s_and_b64 s[0:1], vcc, s[0:1]
	v_add_u32_e32 v71, 33, v0
	v_cndmask_b32_e64 v34, v166, v34, s[0:1]
	v_cmp_le_u32_e64 s[0:1], v71, v136
	s_and_b64 s[0:1], vcc, s[0:1]
	v_add_u32_e32 v71, 34, v0
	v_cndmask_b32_e64 v35, v166, v35, s[0:1]
	v_cmp_le_u32_e64 s[0:1], v71, v136
	s_and_b64 s[0:1], vcc, s[0:1]
	v_add_u32_e32 v71, 35, v0
	v_cndmask_b32_e64 v36, v166, v36, s[0:1]
	v_cmp_le_u32_e64 s[0:1], v71, v136
	s_and_b64 s[0:1], vcc, s[0:1]
	v_add_u32_e32 v71, 36, v0
	v_cndmask_b32_e64 v37, v166, v37, s[0:1]
	v_cmp_le_u32_e64 s[0:1], v71, v136
	s_and_b64 s[0:1], vcc, s[0:1]
	v_add_u32_e32 v71, 37, v0
	v_cndmask_b32_e64 v38, v166, v38, s[0:1]
	v_cmp_le_u32_e64 s[0:1], v71, v136
	s_and_b64 s[0:1], vcc, s[0:1]
	v_add_u32_e32 v71, 38, v0
	v_cndmask_b32_e64 v39, v166, v39, s[0:1]
	v_cmp_le_u32_e64 s[0:1], v71, v136
	s_and_b64 s[0:1], vcc, s[0:1]
	v_or_b32_e32 v71, 39, v70
	v_cndmask_b32_e64 v40, v166, v40, s[0:1]
	v_cmp_le_u32_e64 s[0:1], v71, v136
	s_and_b64 s[0:1], vcc, s[0:1]
	v_add_u32_e32 v71, 48, v0
	v_cndmask_b32_e64 v41, v166, v41, s[0:1]
	v_cmp_le_u32_e64 s[0:1], v71, v136
	s_and_b64 s[0:1], vcc, s[0:1]
	v_add_u32_e32 v71, 49, v0
	v_cndmask_b32_e64 v42, v166, v42, s[0:1]
	v_cmp_le_u32_e64 s[0:1], v71, v136
	s_and_b64 s[0:1], vcc, s[0:1]
	s_nop 0
	v_cndmask_b32_e64 v189, v166, v43, s[0:1]
	v_add_u32_e32 v43, 50, v0
	v_cmp_le_u32_e64 s[0:1], v43, v136
	s_and_b64 s[0:1], vcc, s[0:1]
	v_add_u32_e32 v43, 51, v0
	v_cndmask_b32_e64 v190, v166, v44, s[0:1]
	v_cmp_le_u32_e64 s[0:1], v43, v136
	s_and_b64 s[0:1], vcc, s[0:1]
	v_add_u32_e32 v43, 52, v0
	v_cndmask_b32_e64 v191, v166, v45, s[0:1]
	v_cmp_le_u32_e64 s[0:1], v43, v136
	s_and_b64 s[0:1], vcc, s[0:1]
	v_add_u32_e32 v43, 53, v0
	v_cndmask_b32_e64 v194, v166, v46, s[0:1]
	v_cmp_le_u32_e64 s[0:1], v43, v136
	s_and_b64 s[0:1], vcc, s[0:1]
	v_add_u32_e32 v0, 54, v0
	v_cndmask_b32_e64 v195, v166, v47, s[0:1]
	v_cmp_le_u32_e64 s[0:1], v0, v136
	s_and_b64 s[0:1], vcc, s[0:1]
	v_or_b32_e32 v0, 55, v70
	v_cndmask_b32_e64 v196, v166, v48, s[0:1]
	v_cmp_le_u32_e64 s[0:1], v0, v136
	v_max3_f32 v0, v50, s8, v51
	v_max3_f32 v0, v0, v52, v53
	v_max3_f32 v0, v0, v54, v55
	v_max3_f32 v0, v0, v56, v57
	v_max3_f32 v0, v0, v58, v59
	v_max3_f32 v0, v0, v60, v61
	v_max3_f32 v0, v0, v62, v63
	v_max3_f32 v0, v0, v64, v65
	v_max3_f32 v0, v0, v34, v35
	v_max3_f32 v0, v0, v36, v37
	v_max3_f32 v0, v0, v38, v39
	v_max3_f32 v0, v0, v40, v41
	v_max3_f32 v0, v0, v42, v189
	s_and_b64 vcc, vcc, s[0:1]
	v_max3_f32 v0, v0, v190, v191
	v_cndmask_b32_e32 v197, v166, v49, vcc
	v_max3_f32 v0, v0, v194, v195
	v_max3_f32 v0, v0, v196, v197
	v_mul_f32_e32 v0, 0x3e38aa3b, v0
	v_max_f32_e32 v0, v188, v0
	ds_bpermute_b32 v43, v173, v0
	s_waitcnt lgkmcnt(0)
; #define MFMA(a, b, c) __builtin_amdgcn_mfma_f32_32x32x16_bf16((a), (b), (c), 0, 0, 0)
; DI unsigned pack2(float a, float b) { f32x2_t v = {a, b}; bf16x2_t r = __builtin_convertvector(v, bf16x2_t); return __builtin_bit_cast(unsigned, r); }
; DI float fexp2(float x) { return __builtin_amdgcn_exp2f(x); }
; DI float shx(float v, int m) { return __shfl_xor(v, m, 64); }
; template <int DQK, bool MASKED, int MODE, class MF>
; DI void attn_step(const bf16_t* sK, const bf16_t* sVt, const bf16x8 (&qf)[DQK / 16], f32x16& o0, f32x16& o1, float& m, float& l,
;                   float sc, const MF& mf, int lane, f32x16 (&s)[2], float invl, bool lanevalid = true) {
;     ...
;   const float moff = (!MASKED && !lanevalid) ? 1.0e30f : m;
;   float ps = 0.f;
; #pragma unroll
;   for (int sub = 0; sub < 2; ++sub)
; #pragma unroll
;     for (int q = 0; q < 16; ++q) {
;       float pv = fexp2(__builtin_fmaf(s[sub][q], sc, -moff));
;       if (MASKED && MODE != 0) pv = (s[sub][q] > -1.0e38f) ? pv : 0.f;
;       if (MODE == 2) pv *= invl;
;       s[sub][q] = pv;
;       ps += pv;
;     }
;   if (MODE != 2) {
;     ps += shx(ps, 32);
;     l = l * alpha + ps;
;   }
;   if (MODE == 1) return;
;   if (MODE == 0) {
; #pragma unroll
;     for (int q = 0; q < 16; ++q) { o0[q] *= alpha; o1[q] *= alpha; }
;   }
; #pragma unroll
;   for (int sub = 0; sub < 2; ++sub)
; #pragma unroll
;     for (int s2 = 0; s2 < 2; ++s2) {
;       union { bf16x8 v; unsigned u[4]; } pb;
; #pragma unroll
;       for (int e = 0; e < 4; ++e) pb.u[e] = pack2(s[sub][8 * s2 + 2 * e], s[sub][8 * s2 + 2 * e + 1]);
;       o0 = MFMA(vf[sub][s2][0], pb.v, o0);
;       o1 = MFMA(vf[sub][s2][1], pb.v, o1);
;     }
	v_max_f32_e32 v43, v43, v43
	v_max_f32_e32 v0, v0, v43
	v_fma_f32 v43, v50, s33, -v0
	v_exp_f32_e32 v50, v43
	v_fma_f32 v43, v51, s33, -v0
	v_exp_f32_e32 v51, v43
	v_fma_f32 v43, v52, s33, -v0
	v_exp_f32_e32 v70, v43
	v_fma_f32 v45, v53, s33, -v0
	v_exp_f32_e32 v53, v45
	v_fma_f32 v45, v54, s33, -v0
	v_add_f32_e32 v44, 0, v50
	v_exp_f32_e32 v54, v45
	v_fma_f32 v45, v55, s33, -v0
	v_add_f32_e32 v44, v51, v44
	v_exp_f32_e32 v55, v45
	v_fma_f32 v45, v56, s33, -v0
	v_add_f32_e32 v44, v70, v44
	v_exp_f32_e32 v56, v45
	v_fma_f32 v45, v57, s33, -v0
	v_add_f32_e32 v44, v53, v44
	v_exp_f32_e32 v57, v45
	v_fma_f32 v45, v58, s33, -v0
	v_sub_f32_e32 v43, v141, v0
	v_add_f32_e32 v44, v54, v44
	v_exp_f32_e32 v141, v45
	v_fma_f32 v45, v59, s33, -v0
	v_add_f32_e32 v44, v55, v44
	v_exp_f32_e32 v188, v45
	v_fma_f32 v45, v60, s33, -v0
	v_add_f32_e32 v44, v56, v44
	v_exp_f32_e32 v198, v45
	v_fma_f32 v45, v61, s33, -v0
	v_add_f32_e32 v44, v57, v44
	v_exp_f32_e32 v199, v45
	v_fma_f32 v45, v62, s33, -v0
	v_add_f32_e32 v44, v141, v44
	v_exp_f32_e32 v200, v45
	v_fma_f32 v45, v63, s33, -v0
	v_add_f32_e32 v44, v188, v44
	v_exp_f32_e32 v201, v45
	v_fma_f32 v45, v64, s33, -v0
	v_add_f32_e32 v44, v198, v44
	v_exp_f32_e32 v202, v45
	v_fma_f32 v45, v65, s33, -v0
	v_add_f32_e32 v44, v199, v44
	v_exp_f32_e32 v203, v45
	v_fma_f32 v34, v34, s33, -v0
	v_add_f32_e32 v44, v200, v44
	v_exp_f32_e32 v204, v34
	v_fma_f32 v34, v35, s33, -v0
	v_add_f32_e32 v44, v201, v44
	v_exp_f32_e32 v205, v34
	v_fma_f32 v34, v36, s33, -v0
	v_add_f32_e32 v44, v202, v44
	v_exp_f32_e32 v206, v34
	v_fma_f32 v35, v37, s33, -v0
	v_add_f32_e32 v34, v203, v44
	v_exp_f32_e32 v207, v35
	v_fma_f32 v35, v38, s33, -v0
	v_add_f32_e32 v34, v204, v34
	v_exp_f32_e32 v208, v35
	v_fma_f32 v35, v39, s33, -v0
	v_add_f32_e32 v34, v205, v34
	v_exp_f32_e32 v209, v35
	v_fma_f32 v35, v40, s33, -v0
	v_add_f32_e32 v34, v206, v34
	v_exp_f32_e32 v210, v35
	v_add_f32_e32 v34, v207, v34
	v_add_f32_e32 v34, v208, v34
	v_exp_f32_e32 v52, v43
	v_add_f32_e32 v34, v209, v34
	v_add_f32_e32 v211, v210, v34
	v_fma_f32 v34, v41, s33, -v0
	v_exp_f32_e32 v212, v34
	v_fma_f32 v34, v42, s33, -v0
	v_exp_f32_e32 v213, v34
	v_pk_mul_f32 v[48:49], v[32:33], v[52:53] op_sel_hi:[1,0]
	v_pk_mul_f32 v[46:47], v[30:31], v[52:53] op_sel_hi:[1,0]
	v_pk_mul_f32 v[44:45], v[28:29], v[52:53] op_sel_hi:[1,0]
	v_pk_mul_f32 v[42:43], v[26:27], v[52:53] op_sel_hi:[1,0]
	v_pk_mul_f32 v[40:41], v[24:25], v[52:53] op_sel_hi:[1,0]
	v_pk_mul_f32 v[38:39], v[22:23], v[52:53] op_sel_hi:[1,0]
	v_pk_mul_f32 v[36:37], v[20:21], v[52:53] op_sel_hi:[1,0]
	v_pk_mul_f32 v[34:35], v[18:19], v[52:53] op_sel_hi:[1,0]
	v_pk_mul_f32 v[72:73], v[16:17], v[52:53] op_sel_hi:[1,0]
	v_cvt_pk_bf16_f32 v16, v50, v51
	v_cvt_pk_bf16_f32 v17, v70, v53
	v_cvt_pk_bf16_f32 v18, v54, v55
	v_cvt_pk_bf16_f32 v19, v56, v57
	v_pk_mul_f32 v[70:71], v[14:15], v[52:53] op_sel_hi:[1,0]
	v_pk_mul_f32 v[64:65], v[8:9], v[52:53] op_sel_hi:[1,0]
	v_mfma_f32_32x32x16_bf16 v[34:49], v[66:69], v[16:19], v[34:49]
	v_mul_f32_e64 v68, v12, v52
	v_mul_f32_e64 v69, v13, v52
	v_mul_f32_e64 v66, v10, v52
	v_mul_f32_e64 v67, v11, v52
	v_mul_f32_e64 v62, v6, v52
	v_mul_f32_e64 v63, v7, v52
	v_pk_mul_f32 v[60:61], v[4:5], v[52:53] op_sel_hi:[1,0]
	v_pk_mul_f32 v[58:59], v[2:3], v[52:53] op_sel_hi:[1,0]
	v_add_f32_e32 v2, v212, v211
	v_add_f32_e32 v6, v213, v2
	v_mfma_f32_32x32x16_bf16 v[58:73], v[130:133], v[16:19], v[58:73]
	v_cvt_pk_bf16_f32 v2, v141, v188
	v_cvt_pk_bf16_f32 v3, v198, v199
	v_cvt_pk_bf16_f32 v4, v200, v201
	v_cvt_pk_bf16_f32 v5, v202, v203
	v_fma_f32 v7, v189, s33, -v0
	v_exp_f32_e32 v7, v7
	v_fma_f32 v8, v190, s33, -v0
	v_mfma_f32_32x32x16_bf16 v[34:49], v[126:129], v[2:5], v[34:49]
	v_exp_f32_e32 v8, v8
	v_fma_f32 v9, v191, s33, -v0
	v_exp_f32_e32 v9, v9
	v_fma_f32 v11, v195, s33, -v0
	v_add_f32_e32 v6, v7, v6
	v_exp_f32_e32 v11, v11
	v_fma_f32 v12, v196, s33, -v0
	v_mfma_f32_32x32x16_bf16 v[58:73], v[122:125], v[2:5], v[58:73]
	v_fma_f32 v2, v194, s33, -v0
	v_exp_f32_e32 v10, v2
	v_cvt_pk_bf16_f32 v2, v204, v205
	v_cvt_pk_bf16_f32 v3, v206, v207
	v_cvt_pk_bf16_f32 v4, v208, v209
	v_cvt_pk_bf16_f32 v5, v210, v212
	v_add_f32_e32 v6, v8, v6
	v_exp_f32_e32 v12, v12
	v_mfma_f32_32x32x16_bf16 v[34:49], v[118:121], v[2:5], v[34:49]
	v_fma_f32 v13, v197, s33, -v0
	v_add_f32_e32 v6, v9, v6
	v_exp_f32_e32 v13, v13
	v_add_f32_e32 v6, v10, v6
	v_mfma_f32_32x32x16_bf16 v[58:73], v[114:117], v[2:5], v[58:73]
	v_add_f32_e32 v2, v11, v6
	v_add_f32_e32 v2, v12, v2
	v_add_f32_e32 v6, v13, v2
	v_cvt_pk_bf16_f32 v2, v213, v7
	v_cvt_pk_bf16_f32 v3, v8, v9
	v_cvt_pk_bf16_f32 v4, v10, v11
	v_cvt_pk_bf16_f32 v5, v12, v13
	s_nop 1
	v_mfma_f32_32x32x16_bf16 v[34:49], v[110:113], v[2:5], v[34:49]
	v_mfma_f32_32x32x16_bf16 v[58:73], v[106:109], v[2:5], v[58:73]
	v_fma_f32 v50, v185, v52, v6

; DI void tot_store(float* totL, int tid, const f32x16& a, const f32x16& b, float gi) {
; #pragma unroll
;   for (int k = 0; k < 4; ++k) {
;     f32x4 v0 = {a[4 * k] * gi, a[4 * k + 1] * gi, a[4 * k + 2] * gi, a[4 * k + 3] * gi};
;     f32x4 v1 = {b[4 * k] * gi, b[4 * k + 1] * gi, b[4 * k + 2] * gi, b[4 * k + 3] * gi};
;     *(f32x4*)(totL + ((size_t)(k * 256 + tid)) * 4) = v0;
;     *(f32x4*)(totL + ((size_t)((4 + k) * 256 + tid)) * 4) = v1;
;   }
; }
; DI void tot_addto(float* totL, int tid, f32x16& a, f32x16& b, float gi) {
; #pragma unroll
;   for (int k = 0; k < 4; ++k) {
;     const f32x4 v0 = *(const f32x4*)(totL + ((size_t)(k * 256 + tid)) * 4);
;     const f32x4 v1 = *(const f32x4*)(totL + ((size_t)((4 + k) * 256 + tid)) * 4);
;     a[4 * k] = v0.x + gi * a[4 * k]; a[4 * k + 1] = v0.y + gi * a[4 * k + 1]; a[4 * k + 2] = v0.z + gi * a[4 * k + 2]; a[4 * k + 3] = v0.w + gi * a[4 * k + 3];
; DI void phase_attn_nsa(const Params& P, bf16_t* og, unsigned char* smem, int L, int G) {
;     ...
;       for (int j = 0; j <= jhi; ++j) {
;         const int key0 = j * 64, cb = j & 1;
;         __syncthreads();
;         if (j < jhi) kv64_store(R, sK + (cb ^ 1) * KVB64, sVt + (cb ^ 1) * KVB64, tid);
;         if (j + 1 < jhi) kv64_fetch(R, kb, 256, vb, SEQ, key0 + 128, true, tid);
;         __builtin_amdgcn_sched_barrier(0);
;         if ((selU >> j) & 1u) {
;           const bool lsel = (sel >> j) & 1u;
;           auto mf = [&](int kk) { return lsel && (key0 + kk <= t); };
;           if (key0 + 63 > t0) attn_step<64, true, 0>(sK + cb * KVB64, sVt + cb * KVB64, qf, o0, o1, m, l, sc, mf, lane, s, 0.f);
;           else attn_step<64, false, 0>(sK + cb * KVB64, sVt + cb * KVB64, qf, o0, o1, m, l, sc, mf, lane, s, 0.f, lsel);
;         }
;       }
;       tot_addto(totL, tid, o0, o1, g1 / l);
;       tot_store(totL, tid, o0, o1, 1.f);
;     }
;     {
;       const bf16_t* kb = big + NS_KW + (size_t)b * SEQ * 256 + g * 64;
;       const bf16_t* vb = big + NS_VWT + (size_t)((b * 4 + g) * 64) * SEQ;
;       float m = NEGF, l = 0.f; o_zero(o0, o1);
;       const int jlo = (t0 - 511 > 0 ? t0 - 511 : 0) >> 6, jhi = (t0 + 31) >> 6;
;       KVR R; kv64_fetch(R, kb, 256, vb, SEQ, jlo * 64, true, tid);
;       __syncthreads();
;       kv64_store(R, sK, sVt, tid);
;       if (jlo < jhi) kv64_fetch(R, kb, 256, vb, SEQ, jlo * 64 + 64, true, tid);
.Lmy_hm1345_skip:
	s_cmp_ge_u32 s0, s20
	s_cbranch_scc1 .Lmy_hm1345_s1
	s_xor_b32 s1, s5, 1
	s_mulk_i32 s1, 0x4800
	v_add_u32_e32 v0, s1, v170
	s_waitcnt vmcnt(3)
	ds_write_b128 v0, v[90:93]
	s_waitcnt vmcnt(2)
	ds_write_b128 v0, v[94:97] offset:4608
	s_waitcnt vmcnt(1)
	ds_write_b128 v0, v[98:101] offset:9216
	s_waitcnt vmcnt(0)
	ds_write_b128 v0, v[102:105] offset:13824
.Lmy_hm1345_s1:
	s_cmp_ge_u32 s4, s20
	s_cbranch_scc1 .Lmy_hm1345_s2
	v_add_u32_e32 v36, s44, v169
	v_add_u32_e32 v0, 0x80, v36
	v_lshlrev_b64 v[34:35], 9, v[0:1]
	v_add_u32_e32 v0, 0xa0, v36
	v_lshl_add_u64 v[34:35], v[150:151], 0, v[34:35]
	v_lshlrev_b64 v[36:37], 9, v[0:1]
	s_lshl_b64 s[6:7], s[44:45], 1
	v_lshl_add_u64 v[36:37], v[150:151], 0, v[36:37]
	global_load_dwordx4 v[90:93], v[34:35], off
	global_load_dwordx4 v[94:97], v[36:37], off
	v_lshl_add_u64 v[34:35], v[146:147], 0, s[6:7]
	v_lshl_add_u64 v[36:37], v[148:149], 0, s[6:7]
	global_load_dwordx4 v[98:101], v[34:35], off offset:256
	global_load_dwordx4 v[102:105], v[36:37], off offset:256
.Lmy_hm1345_s2:
	s_branch .LBB0_1355
.LBB0_1357:
	ds_bpermute_b32 v247, v173, v185
	s_waitcnt lgkmcnt(0)
	v_add_f32_e32 v185, v185, v247
	v_readlane_b32 s0, v246, 48
	v_readlane_b32 s1, v246, 49
	v_lshlrev_b32_e32 v0, 1, v187
	v_mov_b32_e32 v141, v1
	v_lshl_add_u64 v[34:35], v[144:145], 1, s[0:1]
	v_readlane_b32 s0, v246, 50
	v_readlane_b32 s1, v246, 51
	v_lshl_add_u64 v[34:35], v[34:35], 0, v[0:1]
	v_div_scale_f32 v72, vcc, v178, v185, v178
	v_lshl_add_u64 v[38:39], v[142:143], 1, s[0:1]
	s_max_i32 s0, s46, 0x1ff
	s_add_i32 s2, s0, 0xfffffe01
	s_and_b32 s44, s2, 0xffffffc0
	v_or_b32_e32 v0, s44, v169
	v_lshlrev_b64 v[36:37], 9, v[0:1]
	v_or_b32_e32 v0, s44, v174
	v_lshl_add_u64 v[36:37], v[34:35], 0, v[36:37]
	v_lshlrev_b64 v[40:41], 9, v[0:1]
	v_lshl_add_u64 v[36:37], v[36:37], 0, v[140:141]
	v_lshl_add_u64 v[40:41], v[34:35], 0, v[40:41]
	v_lshlrev_b32_e32 v0, 1, v186
	v_lshl_add_u64 v[40:41], v[40:41], 0, v[140:141]
	global_load_dwordx4 v[42:45], v[36:37], off
	global_load_dwordx4 v[46:49], v[40:41], off
	v_lshl_add_u64 v[36:37], v[38:39], 0, v[0:1]
	v_lshlrev_b32_e32 v0, 1, v184
	s_lshl_b64 s[0:1], s[44:45], 1
	v_lshl_add_u64 v[38:39], v[38:39], 0, v[0:1]
	v_lshl_add_u64 v[40:41], v[36:37], 0, s[0:1]
	v_lshl_add_u64 v[54:55], v[38:39], 0, s[0:1]
	v_lshl_add_u64 v[40:41], v[40:41], 0, v[140:141]
	v_lshl_add_u64 v[58:59], v[54:55], 0, v[140:141]
	global_load_dwordx4 v[50:53], v[40:41], off
	global_load_dwordx4 v[54:57], v[58:59], off
	v_div_scale_f32 v0, s[0:1], v185, v185, v178
	v_rcp_f32_e32 v73, v0
	ds_read_b128 v[60:63], v180 offset:37376
	ds_read_b128 v[64:67], v180 offset:41472
	ds_read_b128 v[68:71], v180 offset:53760
	s_waitcnt vmcnt(7)
	ds_read_b128 v[90:93], v180 offset:57856
	s_waitcnt vmcnt(6)
	ds_read_b128 v[94:97], v180 offset:45568
	s_waitcnt vmcnt(5)
	ds_read_b128 v[98:101], v180 offset:49664
	s_waitcnt vmcnt(4)
	ds_read_b128 v[102:105], v180 offset:61952
	ds_read_b128 v[106:109], v181 offset:28672
	s_lshr_b32 s2, s2, 6
	v_fma_f32 v110, -v0, v73, 1.0
	v_fmac_f32_e32 v73, v110, v73
	v_mul_f32_e32 v110, v72, v73
	v_fma_f32 v111, -v0, v110, v72
	v_fmac_f32_e32 v110, v111, v73
	v_fma_f32 v0, -v0, v110, v72
	v_div_fmas_f32 v0, v0, v73, v110
	v_div_fixup_f32 v0, v0, v185, v178
	s_waitcnt lgkmcnt(7)
	v_pk_fma_f32 v[18:19], v[0:1], v[18:19], v[60:61] op_sel_hi:[0,1,1]
	v_pk_fma_f32 v[20:21], v[0:1], v[20:21], v[62:63] op_sel_hi:[0,1,1]
	s_cmp_lt_u32 s2, s20
	s_waitcnt lgkmcnt(5)
	v_pk_fma_f32 v[2:3], v[0:1], v[2:3], v[68:69] op_sel_hi:[0,1,1]
	v_pk_fma_f32 v[4:5], v[0:1], v[4:5], v[70:71] op_sel_hi:[0,1,1]
	v_pk_fma_f32 v[22:23], v[0:1], v[22:23], v[64:65] op_sel_hi:[0,1,1]
	v_pk_fma_f32 v[24:25], v[0:1], v[24:25], v[66:67] op_sel_hi:[0,1,1]
	s_waitcnt lgkmcnt(4)
	v_pk_fma_f32 v[6:7], v[0:1], v[6:7], v[90:91] op_sel_hi:[0,1,1]
	v_pk_fma_f32 v[8:9], v[0:1], v[8:9], v[92:93] op_sel_hi:[0,1,1]
	s_waitcnt lgkmcnt(3)
	v_pk_fma_f32 v[26:27], v[0:1], v[26:27], v[94:95] op_sel_hi:[0,1,1]
	v_pk_fma_f32 v[28:29], v[0:1], v[28:29], v[96:97] op_sel_hi:[0,1,1]
	s_waitcnt lgkmcnt(1)
	v_pk_fma_f32 v[10:11], v[0:1], v[10:11], v[102:103] op_sel_hi:[0,1,1]
	v_pk_fma_f32 v[12:13], v[0:1], v[12:13], v[104:105] op_sel_hi:[0,1,1]
	v_pk_fma_f32 v[30:31], v[0:1], v[30:31], v[98:99] op_sel_hi:[0,1,1]
	v_pk_fma_f32 v[32:33], v[0:1], v[32:33], v[100:101] op_sel_hi:[0,1,1]
	s_waitcnt lgkmcnt(0)
	v_pk_fma_f32 v[14:15], v[0:1], v[14:15], v[106:107] op_sel_hi:[0,1,1]
	v_pk_fma_f32 v[16:17], v[0:1], v[16:17], v[108:109] op_sel_hi:[0,1,1]
	ds_write_b128 v180, v[18:21] offset:37376
	ds_write_b128 v180, v[2:5] offset:53760
	ds_write_b128 v180, v[22:25] offset:41472
	ds_write_b128 v180, v[6:9] offset:57856
	ds_write_b128 v180, v[26:29] offset:45568
	ds_write_b128 v180, v[10:13] offset:61952
	ds_write_b128 v180, v[30:33] offset:49664
	ds_write_b128 v181, v[14:17] offset:28672
	s_waitcnt lgkmcnt(0)
	s_barrier
	s_waitcnt vmcnt(3)
	ds_write_b128 v170, v[42:45]
	s_waitcnt vmcnt(2)
	ds_write_b128 v170, v[46:49] offset:4608
	s_waitcnt vmcnt(1)
	ds_write_b128 v170, v[50:53] offset:9216
	s_waitcnt vmcnt(0)
	ds_write_b128 v170, v[54:57] offset:13824
	s_cbranch_scc0 .LBB0_1359
	s_add_i32 s0, s44, 64
	v_or_b32_e32 v0, s0, v169
	v_lshlrev_b64 v[2:3], 9, v[0:1]
	v_or_b32_e32 v0, s0, v174
	v_lshl_add_u64 v[2:3], v[34:35], 0, v[2:3]
	v_lshlrev_b64 v[4:5], 9, v[0:1]
	v_lshl_add_u64 v[2:3], v[2:3], 0, v[140:141]
	v_lshl_add_u64 v[4:5], v[34:35], 0, v[4:5]
	v_lshl_add_u64 v[4:5], v[4:5], 0, v[140:141]
	global_load_dwordx4 v[42:45], v[2:3], off
	global_load_dwordx4 v[46:49], v[4:5], off
	global_load_dwordx4 v[50:53], v[40:41], off offset:128
	global_load_dwordx4 v[54:57], v[58:59], off offset:128

; #define MFMA(a, b, c) __builtin_amdgcn_mfma_f32_32x32x16_bf16((a), (b), (c), 0, 0, 0)
; template <int DQK, bool MASKED, int MODE, class MF>
; DI void attn_step(const bf16_t* sK, const bf16_t* sVt, const bf16x8 (&qf)[DQK / 16], f32x16& o0, f32x16& o1, float& m, float& l,
;                   float sc, const MF& mf, int lane, f32x16 (&s)[2], float invl, bool lanevalid = true) {
;     ...
;   bf16x8 kf[2][DQK / 16];
; #pragma unroll
;   for (int sub = 0; sub < 2; ++sub)
; #pragma unroll
;     for (int ks = 0; ks < DQK / 16; ++ks) kf[sub][ks] = *(const bf16x8*)(sK + (sub * 32 + pr) * KST + ks * 16 + 8 * h);
;   __builtin_amdgcn_sched_barrier(0);
; #pragma unroll
;   for (int q = 0; q < 16; ++q) { s[0][q] = 0.f; s[1][q] = 0.f; }
; #pragma unroll
;   for (int ks = 0; ks < DQK / 16; ++ks) {
;     s[0] = MFMA(kf[0][ks], qf[ks], s[0]);
;     s[1] = MFMA(kf[1][ks], qf[ks], s[1]);
;   }
; DI void phase_attn_nsa(const Params& P, bf16_t* og, unsigned char* smem, int L, int G) {
;     ...
;       for (int j = jlo; j <= jhi; ++j) {
;         const int key0 = j * 64, cb = (j - jlo) & 1;
;         __syncthreads();
;         if (j < jhi) kv64_store(R, sK + (cb ^ 1) * KVB64, sVt + (cb ^ 1) * KVB64, tid);
;         if (j + 1 < jhi) kv64_fetch(R, kb, 256, vb, SEQ, key0 + 128, true, tid);
;         __builtin_amdgcn_sched_barrier(0);
;         auto mf = [&](int kk) { const int key = key0 + kk; return key <= t && key > t - 512; };
;         if (key0 + 63 > t0 || key0 <= t0 + 31 - 512) attn_step<64, true, 0>(sK + cb * KVB64, sVt + cb * KVB64, qf, o0, o1, m, l, sc, mf, lane, s, 0.f);
.LBB0_1361:
	s_add_i32 s0, s2, s4
	s_and_b32 s5, s4, 1
	s_cmp_ge_u32 s0, s20
	s_cselect_b32 s99, 0, 1
	s_add_i32 s0, s0, 1
	s_cmp_ge_u32 s0, s20
	s_cselect_b32 s98, 0, 2
	s_or_b32 s99, s99, s98
	s_xor_b32 s98, s5, 1
	s_mulk_i32 s98, 0x4800
	s_waitcnt lgkmcnt(0)
	s_barrier
.LBB0_1363:
.LBB0_1365:
	s_add_i32 s0, s44, 63
	s_cmp_le_u32 s0, s46
	s_cselect_b64 s[0:1], -1, 0
	s_cmp_gt_i32 s44, s3
	s_cselect_b64 s[6:7], -1, 0
	s_and_b64 s[6:7], s[0:1], s[6:7]
	s_mulk_i32 s5, 0x2400
	v_lshl_add_u32 v98, s5, 1, v153
	s_mov_b64 s[0:1], -1
	s_and_b64 vcc, exec, s[6:7]
	v_max_f32_e32 v149, v148, v148
	s_cbranch_vccnz .LBB0_1367
	v_lshl_add_u32 v0, s5, 1, v172
	ds_read_b128 v[2:5], v0
	ds_read_b128 v[34:37], v0 offset:32
	ds_read_b128 v[38:41], v0 offset:64
	ds_read_b128 v[58:61], v0 offset:96
	ds_read_b128 v[6:9], v0 offset:4608
	ds_read_b128 v[62:65], v0 offset:4640
	ds_read_b128 v[66:69], v0 offset:4672
	ds_read_b128 v[184:187], v0 offset:4704
	s_waitcnt lgkmcnt(7)
	v_mfma_f32_32x32x16_bf16 v[18:33], v[2:5], v[74:77], 0
	v_lshlrev_b32_e32 v0, 1, v171
	s_waitcnt lgkmcnt(3)
	v_mfma_f32_32x32x16_bf16 v[2:17], v[6:9], v[74:77], 0
	v_mfma_f32_32x32x16_bf16 v[18:33], v[34:37], v[78:81], v[18:33]
	v_add3_u32 v34, v98, v175, v0
	v_add3_u32 v0, v98, v177, v0
	s_bitcmp1_b32 s99, 0
	s_cbranch_scc0 .Lmy_hm1361_0_ns
	v_add_u32_e32 v247, s98, v170
	s_waitcnt vmcnt(3)
	ds_write_b128 v247, v[42:45]
	s_waitcnt vmcnt(2)
	ds_write_b128 v247, v[46:49] offset:4608
	s_waitcnt vmcnt(1)
	ds_write_b128 v247, v[50:53] offset:9216
	s_waitcnt vmcnt(0)
	ds_write_b128 v247, v[54:57] offset:13824
	s_branch .Lmy_hm1361_0_sd

; template <int DQK, bool MASKED, int MODE, class MF>
; DI void attn_step(const bf16_t* sK, const bf16_t* sVt, const bf16x8 (&qf)[DQK / 16], f32x16& o0, f32x16& o1, float& m, float& l,
;                   float sc, const MF& mf, int lane, f32x16 (&s)[2], float invl, bool lanevalid = true) {
;     ...
;   bf16x8 vf[2][2][2];
;   if (MODE != 1) {
; #pragma unroll
;     for (int sub = 0; sub < 2; ++sub)
; #pragma unroll
;       for (int s2 = 0; s2 < 2; ++s2) {
;         vf[sub][s2][0] = *(const bf16x8*)(sVt + r * 72 + sub * 32 + s2 * 16 + 8 * h);
;         vf[sub][s2][1] = *(const bf16x8*)(sVt + (32 + r) * 72 + sub * 32 + s2 * 16 + 8 * h);
;       }
;     __builtin_amdgcn_sched_barrier(0);
;   }
;   float mxr = -3.0e38f;
; #pragma unroll
;   for (int sub = 0; sub < 2; ++sub)
; #pragma unroll
;     for (int q = 0; q < 16; ++q) {
;       if (MASKED) { const int kk = sub * 32 + 16 * (q >> 3) + 8 * h + (q & 7); s[sub][q] = mf(kk) ? s[sub][q] : -3.0e38f; }
;       if (MODE != 2) mxr = fmaxf(mxr, s[sub][q]);
;     }
.Lmy_hm1361_0_sd:
	s_bitcmp1_b32 s99, 1
	s_cbranch_scc0 .Lmy_hm1361_0_np
	v_mov_b32_e32 v249, 0
	v_add_u32_e32 v252, s44, v169
	v_add_u32_e32 v248, 0x80, v252
	v_lshlrev_b64 v[250:251], 9, v[248:249]
	v_add_u32_e32 v248, 0xa0, v252
	v_lshl_add_u64 v[250:251], v[102:103], 0, v[250:251]
	v_lshlrev_b64 v[252:253], 9, v[248:249]
	s_lshl_b64 s[100:101], s[44:45], 1
	v_lshl_add_u64 v[252:253], v[102:103], 0, v[252:253]
	global_load_dwordx4 v[42:45], v[250:251], off
	global_load_dwordx4 v[46:49], v[252:253], off
	v_lshl_add_u64 v[250:251], v[104:105], 0, s[100:101]
	v_lshl_add_u64 v[252:253], v[106:107], 0, s[100:101]
	global_load_dwordx4 v[50:53], v[250:251], off offset:256
	global_load_dwordx4 v[54:57], v[252:253], off offset:256
.Lmy_hm1361_0_np:
	s_waitcnt lgkmcnt(6)
	v_mfma_f32_32x32x16_bf16 v[2:17], v[62:65], v[78:81], v[2:17]
	v_mfma_f32_32x32x16_bf16 v[18:33], v[38:41], v[82:85], v[18:33]
	s_waitcnt lgkmcnt(5)
	v_mfma_f32_32x32x16_bf16 v[2:17], v[66:69], v[82:85], v[2:17]
	v_mfma_f32_32x32x16_bf16 v[18:33], v[58:61], v[86:89], v[18:33]
	ds_read_b128 v[94:97], v34 offset:9216
	ds_read_b128 v[70:73], v34 offset:9248
	ds_read_b128 v[90:93], v0 offset:9216
	ds_read_b128 v[66:69], v0 offset:9248
	ds_read_b128 v[62:65], v34 offset:9280
	ds_read_b128 v[38:41], v34 offset:9312
	ds_read_b128 v[58:61], v0 offset:9280
	ds_read_b128 v[34:37], v0 offset:9312
	s_waitcnt lgkmcnt(12)
	v_mfma_f32_32x32x16_bf16 v[2:17], v[184:187], v[86:89], v[2:17]
	v_add_u32_e32 v0, s44, v171
	v_cmp_le_u32_e32 vcc, v0, v136
	v_cmp_gt_i32_e64 s[0:1], v0, v146
	s_and_b64 vcc, vcc, s[0:1]
	v_cndmask_b32_e32 v18, v166, v18, vcc
	v_cmp_lt_u32_e32 vcc, v0, v136
	v_cmp_ge_i32_e64 s[0:1], v0, v146
	s_and_b64 vcc, vcc, s[0:1]
	v_add_u32_e32 v99, 2, v0
	v_cndmask_b32_e32 v19, v166, v19, vcc
	v_cmp_le_u32_e32 vcc, v99, v136
	v_cmp_gt_i32_e64 s[0:1], v99, v146
	s_and_b64 vcc, vcc, s[0:1]
	v_add_u32_e32 v99, 3, v0
	v_cndmask_b32_e32 v20, v166, v20, vcc
	v_cmp_le_u32_e32 vcc, v99, v136
	v_cmp_gt_i32_e64 s[0:1], v99, v146
	s_and_b64 vcc, vcc, s[0:1]
	v_add_u32_e32 v99, 4, v0
	v_cndmask_b32_e32 v21, v166, v21, vcc
	v_cmp_le_u32_e32 vcc, v99, v136
	v_cmp_gt_i32_e64 s[0:1], v99, v146
	s_and_b64 vcc, vcc, s[0:1]
	v_add_u32_e32 v99, 5, v0
	v_cndmask_b32_e32 v22, v166, v22, vcc
	v_cmp_le_u32_e32 vcc, v99, v136
	v_cmp_gt_i32_e64 s[0:1], v99, v146
	s_and_b64 vcc, vcc, s[0:1]
	v_add_u32_e32 v99, 6, v0
	v_cndmask_b32_e32 v23, v166, v23, vcc
	v_cmp_le_u32_e32 vcc, v99, v136
	v_cmp_gt_i32_e64 s[0:1], v99, v146
	v_add_u32_e32 v99, s44, v139
	s_and_b64 vcc, vcc, s[0:1]
	v_or_b32_e32 v100, 7, v99
	v_cndmask_b32_e32 v24, v166, v24, vcc
	v_cmp_le_u32_e32 vcc, v100, v136
	v_cmp_gt_i32_e64 s[0:1], v100, v146
	s_and_b64 vcc, vcc, s[0:1]
	v_add_u32_e32 v100, 16, v0
	v_cndmask_b32_e32 v25, v166, v25, vcc
	v_cmp_le_u32_e32 vcc, v100, v136
	v_cmp_gt_i32_e64 s[0:1], v100, v146
	s_and_b64 vcc, vcc, s[0:1]
	v_add_u32_e32 v100, 17, v0
	v_cndmask_b32_e32 v26, v166, v26, vcc
	v_cmp_le_u32_e32 vcc, v100, v136
	v_cmp_gt_i32_e64 s[0:1], v100, v146
	s_and_b64 vcc, vcc, s[0:1]
	v_add_u32_e32 v100, 18, v0
	v_cndmask_b32_e32 v27, v166, v27, vcc
	v_cmp_le_u32_e32 vcc, v100, v136
	v_cmp_gt_i32_e64 s[0:1], v100, v146
	s_and_b64 vcc, vcc, s[0:1]
	v_add_u32_e32 v100, 19, v0
	v_cndmask_b32_e32 v28, v166, v28, vcc
	v_cmp_le_u32_e32 vcc, v100, v136
	v_cmp_gt_i32_e64 s[0:1], v100, v146
	s_and_b64 vcc, vcc, s[0:1]
	v_add_u32_e32 v100, 20, v0
	v_cndmask_b32_e32 v29, v166, v29, vcc
	v_cmp_le_u32_e32 vcc, v100, v136
	v_cmp_gt_i32_e64 s[0:1], v100, v146
	s_and_b64 vcc, vcc, s[0:1]
	v_add_u32_e32 v100, 21, v0
	v_cndmask_b32_e32 v30, v166, v30, vcc
	v_cmp_le_u32_e32 vcc, v100, v136
	v_cmp_gt_i32_e64 s[0:1], v100, v146
	s_and_b64 vcc, vcc, s[0:1]
	v_add_u32_e32 v100, 22, v0
	v_cndmask_b32_e32 v31, v166, v31, vcc
	v_cmp_le_u32_e32 vcc, v100, v136
	v_cmp_gt_i32_e64 s[0:1], v100, v146
	s_and_b64 vcc, vcc, s[0:1]
	v_or_b32_e32 v100, 23, v99
	v_cndmask_b32_e32 v32, v166, v32, vcc
	v_cmp_le_u32_e32 vcc, v100, v136
	v_cmp_gt_i32_e64 s[0:1], v100, v146
	s_and_b64 vcc, vcc, s[0:1]
	v_add_u32_e32 v100, 32, v0
	v_cndmask_b32_e32 v33, v166, v33, vcc
	v_cmp_le_u32_e32 vcc, v100, v136
	v_cmp_gt_i32_e64 s[0:1], v100, v146
	s_and_b64 vcc, vcc, s[0:1]
	v_add_u32_e32 v100, 33, v0
	v_cndmask_b32_e32 v2, v166, v2, vcc
	v_cmp_le_u32_e32 vcc, v100, v136
	v_cmp_gt_i32_e64 s[0:1], v100, v146
	s_and_b64 vcc, vcc, s[0:1]
	v_add_u32_e32 v100, 34, v0
	v_cndmask_b32_e32 v3, v166, v3, vcc
	v_cmp_le_u32_e32 vcc, v100, v136
	v_cmp_gt_i32_e64 s[0:1], v100, v146
	s_and_b64 vcc, vcc, s[0:1]
	v_add_u32_e32 v100, 35, v0
	v_cndmask_b32_e32 v4, v166, v4, vcc
	v_cmp_le_u32_e32 vcc, v100, v136
	v_cmp_gt_i32_e64 s[0:1], v100, v146
	s_and_b64 vcc, vcc, s[0:1]
	v_add_u32_e32 v100, 36, v0
	v_cndmask_b32_e32 v5, v166, v5, vcc
	v_cmp_le_u32_e32 vcc, v100, v136
	v_cmp_gt_i32_e64 s[0:1], v100, v146
	s_and_b64 vcc, vcc, s[0:1]
	v_add_u32_e32 v100, 37, v0
	v_cndmask_b32_e32 v6, v166, v6, vcc
	v_cmp_le_u32_e32 vcc, v100, v136
	v_cmp_gt_i32_e64 s[0:1], v100, v146
	s_and_b64 vcc, vcc, s[0:1]
	v_add_u32_e32 v100, 38, v0
	v_cndmask_b32_e32 v7, v166, v7, vcc
	v_cmp_le_u32_e32 vcc, v100, v136
	v_cmp_gt_i32_e64 s[0:1], v100, v146
	s_and_b64 vcc, vcc, s[0:1]
	v_or_b32_e32 v100, 39, v99
	v_cndmask_b32_e32 v8, v166, v8, vcc
	v_cmp_le_u32_e32 vcc, v100, v136
	v_cmp_gt_i32_e64 s[0:1], v100, v146
	s_and_b64 vcc, vcc, s[0:1]
	v_add_u32_e32 v100, 48, v0
	v_cndmask_b32_e32 v9, v166, v9, vcc
	v_cmp_le_u32_e32 vcc, v100, v136
	v_cmp_gt_i32_e64 s[0:1], v100, v146
	s_and_b64 vcc, vcc, s[0:1]
	v_add_u32_e32 v100, 49, v0
	v_cndmask_b32_e32 v10, v166, v10, vcc
	v_cmp_le_u32_e32 vcc, v100, v136
; #define MFMA(a, b, c) __builtin_amdgcn_mfma_f32_32x32x16_bf16((a), (b), (c), 0, 0, 0)
; DI unsigned pack2(float a, float b) { f32x2_t v = {a, b}; bf16x2_t r = __builtin_convertvector(v, bf16x2_t); return __builtin_bit_cast(unsigned, r); }
; DI float fexp2(float x) { return __builtin_amdgcn_exp2f(x); }
; DI float shx(float v, int m) { return __shfl_xor(v, m, 64); }
; template <int DQK, bool MASKED, int MODE, class MF>
; DI void attn_step(const bf16_t* sK, const bf16_t* sVt, const bf16x8 (&qf)[DQK / 16], f32x16& o0, f32x16& o1, float& m, float& l,
;                   float sc, const MF& mf, int lane, f32x16 (&s)[2], float invl, bool lanevalid = true) {
;     ...
;   float mxr = -3.0e38f;
; #pragma unroll
;   for (int sub = 0; sub < 2; ++sub)
; #pragma unroll
;     for (int q = 0; q < 16; ++q) {
;       if (MASKED) { const int kk = sub * 32 + 16 * (q >> 3) + 8 * h + (q & 7); s[sub][q] = mf(kk) ? s[sub][q] : -3.0e38f; }
;       if (MODE != 2) mxr = fmaxf(mxr, s[sub][q]);
;     }
;   float alpha = 1.f;
;   if (MODE != 2) {
;     float mx = fmaxf(m, mxr * sc);
;     mx = fmaxf(mx, shx(mx, 32));
;     if (!MASKED) mx = lanevalid ? mx : m;
;     alpha = fexp2(m - mx);
;     m = mx;
;   }
;   const float moff = (!MASKED && !lanevalid) ? 1.0e30f : m;
;   float ps = 0.f;
; #pragma unroll
;   for (int sub = 0; sub < 2; ++sub)
; #pragma unroll
;     for (int q = 0; q < 16; ++q) {
;       float pv = fexp2(__builtin_fmaf(s[sub][q], sc, -moff));
;       if (MASKED && MODE != 0) pv = (s[sub][q] > -1.0e38f) ? pv : 0.f;
;       if (MODE == 2) pv *= invl;
;       s[sub][q] = pv;
;       ps += pv;
;     }
;   if (MODE != 2) {
;     ps += shx(ps, 32);
;     l = l * alpha + ps;
;   }
;   if (MODE == 1) return;
;   if (MODE == 0) {
; #pragma unroll
;     for (int q = 0; q < 16; ++q) { o0[q] *= alpha; o1[q] *= alpha; }
;   }
; #pragma unroll
;   for (int sub = 0; sub < 2; ++sub)
; #pragma unroll
;     for (int s2 = 0; s2 < 2; ++s2) {
;       union { bf16x8 v; unsigned u[4]; } pb;
; #pragma unroll
;       for (int e = 0; e < 4; ++e) pb.u[e] = pack2(s[sub][8 * s2 + 2 * e], s[sub][8 * s2 + 2 * e + 1]);
;       o0 = MFMA(vf[sub][s2][0], pb.v, o0);
;       o1 = MFMA(vf[sub][s2][1], pb.v, o1);
;     }
	v_cmp_gt_i32_e64 s[0:1], v100, v146
	s_and_b64 vcc, vcc, s[0:1]
	v_cndmask_b32_e32 v101, v166, v11, vcc
	v_add_u32_e32 v11, 50, v0
	v_cmp_le_u32_e32 vcc, v11, v136
	v_cmp_gt_i32_e64 s[0:1], v11, v146
	s_and_b64 vcc, vcc, s[0:1]
	v_add_u32_e32 v11, 51, v0
	v_cndmask_b32_e32 v150, v166, v12, vcc
	v_cmp_le_u32_e32 vcc, v11, v136
	v_cmp_gt_i32_e64 s[0:1], v11, v146
	s_and_b64 vcc, vcc, s[0:1]
	v_add_u32_e32 v11, 52, v0
	v_cndmask_b32_e32 v151, v166, v13, vcc
	v_cmp_le_u32_e32 vcc, v11, v136
	v_cmp_gt_i32_e64 s[0:1], v11, v146
	s_and_b64 vcc, vcc, s[0:1]
	v_add_u32_e32 v11, 53, v0
	v_cndmask_b32_e32 v174, v166, v14, vcc
	v_cmp_le_u32_e32 vcc, v11, v136
	v_cmp_gt_i32_e64 s[0:1], v11, v146
	s_and_b64 vcc, vcc, s[0:1]
	v_add_u32_e32 v0, 54, v0
	v_cndmask_b32_e32 v178, v166, v15, vcc
	v_cmp_le_u32_e32 vcc, v0, v136
	v_cmp_gt_i32_e64 s[0:1], v0, v146
	s_and_b64 vcc, vcc, s[0:1]
	v_or_b32_e32 v0, 55, v99
	v_cndmask_b32_e32 v183, v166, v16, vcc
	v_cmp_le_u32_e32 vcc, v0, v136
	v_cmp_gt_i32_e64 s[0:1], v0, v146
	v_max3_f32 v0, v18, s8, v19
	v_max3_f32 v0, v0, v20, v21
	v_max3_f32 v0, v0, v22, v23
	v_max3_f32 v0, v0, v24, v25
	v_max3_f32 v0, v0, v26, v27
	v_max3_f32 v0, v0, v28, v29
	v_max3_f32 v0, v0, v30, v31
	v_max3_f32 v0, v0, v32, v33
	v_max3_f32 v0, v0, v2, v3
	v_max3_f32 v0, v0, v4, v5
	v_max3_f32 v0, v0, v6, v7
	v_max3_f32 v0, v0, v8, v9
	v_max3_f32 v0, v0, v10, v101
	s_and_b64 vcc, vcc, s[0:1]
	v_max3_f32 v0, v0, v150, v151
	v_cndmask_b32_e32 v99, v166, v17, vcc
	v_max3_f32 v0, v0, v174, v178
	v_max3_f32 v0, v0, v183, v99
	v_mul_f32_e32 v0, 0x3e38aa3b, v0
	v_max_f32_e32 v0, v149, v0
	ds_bpermute_b32 v11, v173, v0
	s_mov_b64 s[0:1], 0
	s_waitcnt lgkmcnt(0)
	v_max_f32_e32 v11, v11, v11
	v_max_f32_e32 v0, v0, v11
	v_fma_f32 v11, v18, s33, -v0
	v_exp_f32_e32 v18, v11
	v_fma_f32 v11, v19, s33, -v0
	v_exp_f32_e32 v19, v11
	v_fma_f32 v11, v20, s33, -v0
	v_exp_f32_e32 v20, v11
	v_fma_f32 v13, v21, s33, -v0
	v_exp_f32_e32 v21, v13
	v_fma_f32 v13, v22, s33, -v0
	v_add_f32_e32 v12, 0, v18
	v_exp_f32_e32 v22, v13
	v_fma_f32 v13, v23, s33, -v0
	v_add_f32_e32 v12, v19, v12
	v_exp_f32_e32 v23, v13
	v_fma_f32 v13, v24, s33, -v0
	v_add_f32_e32 v12, v20, v12
	v_exp_f32_e32 v24, v13
	v_fma_f32 v13, v25, s33, -v0
	v_add_f32_e32 v12, v21, v12
	v_exp_f32_e32 v25, v13
	v_fma_f32 v13, v26, s33, -v0
	v_add_f32_e32 v12, v22, v12
	v_exp_f32_e32 v188, v13
	v_fma_f32 v13, v27, s33, -v0
	v_add_f32_e32 v12, v23, v12
	v_exp_f32_e32 v189, v13
	v_fma_f32 v13, v28, s33, -v0
	v_add_f32_e32 v12, v24, v12
	v_exp_f32_e32 v190, v13
	v_fma_f32 v13, v29, s33, -v0
	v_add_f32_e32 v12, v25, v12
	v_exp_f32_e32 v191, v13
	v_fma_f32 v13, v30, s33, -v0
	v_add_f32_e32 v12, v188, v12
	v_exp_f32_e32 v194, v13
	v_fma_f32 v13, v31, s33, -v0
	v_add_f32_e32 v12, v189, v12
	v_exp_f32_e32 v195, v13
	v_fma_f32 v13, v32, s33, -v0
	v_add_f32_e32 v12, v190, v12
	v_exp_f32_e32 v196, v13
	v_fma_f32 v13, v33, s33, -v0
	v_add_f32_e32 v12, v191, v12
	v_exp_f32_e32 v197, v13
	v_fma_f32 v2, v2, s33, -v0
	v_add_f32_e32 v12, v194, v12
	v_exp_f32_e32 v198, v2
	v_fma_f32 v2, v3, s33, -v0
	v_add_f32_e32 v12, v195, v12
	v_exp_f32_e32 v199, v2
	v_fma_f32 v2, v4, s33, -v0
	v_add_f32_e32 v12, v196, v12
	v_exp_f32_e32 v200, v2
	v_fma_f32 v3, v5, s33, -v0
	v_add_f32_e32 v2, v197, v12
	v_exp_f32_e32 v201, v3
	v_fma_f32 v3, v6, s33, -v0
	v_add_f32_e32 v2, v198, v2
	v_exp_f32_e32 v202, v3
	v_fma_f32 v3, v7, s33, -v0
	v_add_f32_e32 v2, v199, v2
	v_exp_f32_e32 v203, v3
	v_fma_f32 v3, v8, s33, -v0
	v_add_f32_e32 v2, v200, v2
	v_exp_f32_e32 v204, v3
	v_sub_f32_e32 v11, v148, v0
	v_add_f32_e32 v2, v201, v2
	v_add_f32_e32 v2, v202, v2
	v_exp_f32_e32 v100, v11
	v_add_f32_e32 v2, v203, v2
	v_add_f32_e32 v205, v204, v2
	v_fma_f32 v2, v9, s33, -v0
	v_exp_f32_e32 v206, v2
	v_fma_f32 v2, v10, s33, -v0
	v_exp_f32_e32 v207, v2
	v_pk_mul_f32 v[16:17], v[144:145], v[100:101] op_sel_hi:[1,0]
	v_pk_mul_f32 v[14:15], v[140:141], v[100:101] op_sel_hi:[1,0]
	v_pk_mul_f32 v[12:13], v[132:133], v[100:101] op_sel_hi:[1,0]
	v_pk_mul_f32 v[10:11], v[130:131], v[100:101] op_sel_hi:[1,0]
	v_pk_mul_f32 v[8:9], v[128:129], v[100:101] op_sel_hi:[1,0]
	v_pk_mul_f32 v[6:7], v[126:127], v[100:101] op_sel_hi:[1,0]
	v_pk_mul_f32 v[4:5], v[124:125], v[100:101] op_sel_hi:[1,0]
	v_pk_mul_f32 v[2:3], v[122:123], v[100:101] op_sel_hi:[1,0]
	v_pk_mul_f32 v[32:33], v[142:143], v[100:101] op_sel_hi:[1,0]
	v_cvt_pk_bf16_f32 v184, v18, v19
	v_cvt_pk_bf16_f32 v185, v20, v21
	v_cvt_pk_bf16_f32 v186, v22, v23
	v_cvt_pk_bf16_f32 v187, v24, v25
	v_pk_mul_f32 v[30:31], v[120:121], v[100:101] op_sel_hi:[1,0]
	v_pk_mul_f32 v[28:29], v[118:119], v[100:101] op_sel_hi:[1,0]
	v_pk_mul_f32 v[26:27], v[116:117], v[100:101] op_sel_hi:[1,0]
	v_pk_mul_f32 v[24:25], v[114:115], v[100:101] op_sel_hi:[1,0]
	v_pk_mul_f32 v[22:23], v[112:113], v[100:101] op_sel_hi:[1,0]
	v_pk_mul_f32 v[20:21], v[110:111], v[100:101] op_sel_hi:[1,0]
	v_pk_mul_f32 v[18:19], v[108:109], v[100:101] op_sel_hi:[1,0]
	v_mfma_f32_32x32x16_bf16 v[2:17], v[94:97], v[184:187], v[2:17]
	v_fma_f32 v95, v101, s33, -v0
	v_mfma_f32_32x32x16_bf16 v[18:33], v[90:93], v[184:187], v[18:33]
	v_add_f32_e32 v90, v206, v205
	v_add_f32_e32 v94, v207, v90
	v_cvt_pk_bf16_f32 v90, v188, v189
	v_cvt_pk_bf16_f32 v91, v190, v191
	v_cvt_pk_bf16_f32 v92, v194, v195
	v_cvt_pk_bf16_f32 v93, v196, v197
	s_nop 1
	v_mfma_f32_32x32x16_bf16 v[2:17], v[70:73], v[90:93], v[2:17]
	v_exp_f32_e32 v70, v95
	v_fma_f32 v71, v150, s33, -v0
	v_exp_f32_e32 v71, v71
	v_fma_f32 v72, v151, s33, -v0
	v_exp_f32_e32 v72, v72
	v_add_f32_e32 v73, v70, v94
	v_add_f32_e32 v73, v71, v73
	v_mfma_f32_32x32x16_bf16 v[18:33], v[66:69], v[90:93], v[18:33]
	v_fma_f32 v66, v174, s33, -v0
	v_exp_f32_e32 v90, v66
	v_cvt_pk_bf16_f32 v66, v198, v199
	v_cvt_pk_bf16_f32 v67, v200, v201
	v_cvt_pk_bf16_f32 v68, v202, v203
	v_cvt_pk_bf16_f32 v69, v204, v206
	v_add_f32_e32 v73, v72, v73
	s_nop 0
	v_mfma_f32_32x32x16_bf16 v[2:17], v[62:65], v[66:69], v[2:17]
	v_fma_f32 v63, v178, s33, -v0
	v_exp_f32_e32 v63, v63
	v_fma_f32 v64, v183, s33, -v0
	v_exp_f32_e32 v64, v64
	v_fma_f32 v65, v99, s33, -v0
	v_exp_f32_e32 v65, v65
	v_add_f32_e32 v62, v90, v73
	v_mfma_f32_32x32x16_bf16 v[18:33], v[58:61], v[66:69], v[18:33]
	v_add_f32_e32 v58, v63, v62
	v_add_f32_e32 v58, v64, v58
	v_add_f32_e32 v62, v65, v58
	v_cvt_pk_bf16_f32 v58, v207, v70
	v_cvt_pk_bf16_f32 v59, v71, v72
	v_cvt_pk_bf16_f32 v60, v90, v63
	v_cvt_pk_bf16_f32 v61, v64, v65
	s_nop 1
	v_mfma_f32_32x32x16_bf16 v[2:17], v[38:41], v[58:61], v[2:17]
	s_nop 1
	v_mfma_f32_32x32x16_bf16 v[18:33], v[34:37], v[58:61], v[18:33]
	v_fma_f32 v40, v147, v100, v62
; #define MFMA(a, b, c) __builtin_amdgcn_mfma_f32_32x32x16_bf16((a), (b), (c), 0, 0, 0)
; template <int DQK, bool MASKED, int MODE, class MF>
; DI void attn_step(const bf16_t* sK, const bf16_t* sVt, const bf16x8 (&qf)[DQK / 16], f32x16& o0, f32x16& o1, float& m, float& l,
;                   float sc, const MF& mf, int lane, f32x16 (&s)[2], float invl, bool lanevalid = true) {
;     ...
;   bf16x8 kf[2][DQK / 16];
; #pragma unroll
;   for (int sub = 0; sub < 2; ++sub)
; #pragma unroll
;     for (int ks = 0; ks < DQK / 16; ++ks) kf[sub][ks] = *(const bf16x8*)(sK + (sub * 32 + pr) * KST + ks * 16 + 8 * h);
;   __builtin_amdgcn_sched_barrier(0);
; #pragma unroll
;   for (int q = 0; q < 16; ++q) { s[0][q] = 0.f; s[1][q] = 0.f; }
; #pragma unroll
;   for (int ks = 0; ks < DQK / 16; ++ks) {
;     s[0] = MFMA(kf[0][ks], qf[ks], s[0]);
;     s[1] = MFMA(kf[1][ks], qf[ks], s[1]);
;   }
; DI void phase_attn_nsa(const Params& P, bf16_t* og, unsigned char* smem, int L, int G) {
;     ...
;         if (key0 + 63 > t0 || key0 <= t0 + 31 - 512) attn_step<64, true, 0>(sK + cb * KVB64, sVt + cb * KVB64, qf, o0, o1, m, l, sc, mf, lane, s, 0.f);
;         else attn_step<64, false, 0>(sK + cb * KVB64, sVt + cb * KVB64, qf, o0, o1, m, l, sc, mf, lane, s, 0.f);
.LBB0_1367:
	s_andn2_b64 vcc, exec, s[0:1]
	s_cbranch_vccnz .LBB0_1369
	v_lshl_add_u32 v0, s5, 1, v182
	s_nop 3
	ds_read_b128 v[2:5], v0
	s_nop 3
	ds_read_b128 v[18:21], v0 offset:32
	ds_read_b128 v[22:25], v0 offset:64
	ds_read_b128 v[58:61], v0 offset:96
	ds_read_b128 v[26:29], v0 offset:4608
	ds_read_b128 v[62:65], v0 offset:4640
	ds_read_b128 v[66:69], v0 offset:4672
	ds_read_b128 v[184:187], v0 offset:4704
	s_waitcnt lgkmcnt(7)
	v_mfma_f32_32x32x16_bf16 v[2:17], v[2:5], v[74:77], 0
	v_add3_u32 v0, v98, v175, v138
	s_waitcnt lgkmcnt(3)
	v_mfma_f32_32x32x16_bf16 v[26:41], v[26:29], v[74:77], 0
	v_mfma_f32_32x32x16_bf16 v[2:17], v[18:21], v[78:81], v[2:17]
	s_bitcmp1_b32 s99, 0
	s_cbranch_scc0 .Lmy_hm1361_1_ns
	v_add_u32_e32 v247, s98, v170
	s_waitcnt vmcnt(3)
	ds_write_b128 v247, v[42:45]
	s_waitcnt vmcnt(2)
	ds_write_b128 v247, v[46:49] offset:4608
	s_waitcnt vmcnt(1)
	ds_write_b128 v247, v[50:53] offset:9216
	s_waitcnt vmcnt(0)
	ds_write_b128 v247, v[54:57] offset:13824
	s_branch .Lmy_hm1361_1_sd

; #define MFMA(a, b, c) __builtin_amdgcn_mfma_f32_32x32x16_bf16((a), (b), (c), 0, 0, 0)
; DI float fexp2(float x) { return __builtin_amdgcn_exp2f(x); }
; template <int DQK, bool MASKED, int MODE, class MF>
; DI void attn_step(const bf16_t* sK, const bf16_t* sVt, const bf16x8 (&qf)[DQK / 16], f32x16& o0, f32x16& o1, float& m, float& l,
;                   float sc, const MF& mf, int lane, f32x16 (&s)[2], float invl, bool lanevalid = true) {
;     ...
;   bf16x8 vf[2][2][2];
;   if (MODE != 1) {
; #pragma unroll
;     for (int sub = 0; sub < 2; ++sub)
; #pragma unroll
;       for (int s2 = 0; s2 < 2; ++s2) {
;         vf[sub][s2][0] = *(const bf16x8*)(sVt + r * 72 + sub * 32 + s2 * 16 + 8 * h);
;         vf[sub][s2][1] = *(const bf16x8*)(sVt + (32 + r) * 72 + sub * 32 + s2 * 16 + 8 * h);
;       }
;     __builtin_amdgcn_sched_barrier(0);
;   }
;   float mxr = -3.0e38f;
; #pragma unroll
;   for (int sub = 0; sub < 2; ++sub)
; #pragma unroll
;     for (int q = 0; q < 16; ++q) {
;       if (MASKED) { const int kk = sub * 32 + 16 * (q >> 3) + 8 * h + (q & 7); s[sub][q] = mf(kk) ? s[sub][q] : -3.0e38f; }
;       if (MODE != 2) mxr = fmaxf(mxr, s[sub][q]);
;     }
;   float alpha = 1.f;
;   if (MODE != 2) {
;     float mx = fmaxf(m, mxr * sc);
;     mx = fmaxf(mx, shx(mx, 32));
;     if (!MASKED) mx = lanevalid ? mx : m;
;     alpha = fexp2(m - mx);
;     m = mx;
;   }
;   const float moff = (!MASKED && !lanevalid) ? 1.0e30f : m;
;   float ps = 0.f;
; #pragma unroll
;   for (int sub = 0; sub < 2; ++sub)
; #pragma unroll
;     for (int q = 0; q < 16; ++q) {
;       float pv = fexp2(__builtin_fmaf(s[sub][q], sc, -moff));
;       if (MASKED && MODE != 0) pv = (s[sub][q] > -1.0e38f) ? pv : 0.f;
;       if (MODE == 2) pv *= invl;
;       s[sub][q] = pv;
;       ps += pv;
;     }
;   if (MODE != 2) {
;     ps += shx(ps, 32);
;     l = l * alpha + ps;
;   }
;   if (MODE == 1) return;
;   if (MODE == 0) {
; #pragma unroll
;     for (int q = 0; q < 16; ++q) { o0[q] *= alpha; o1[q] *= alpha; }
;   }
; #pragma unroll
;   for (int sub = 0; sub < 2; ++sub)
; #pragma unroll
;     for (int s2 = 0; s2 < 2; ++s2) {
;       union { bf16x8 v; unsigned u[4]; } pb;
; #pragma unroll
;       for (int e = 0; e < 4; ++e) pb.u[e] = pack2(s[sub][8 * s2 + 2 * e], s[sub][8 * s2 + 2 * e + 1]);
;       o0 = MFMA(vf[sub][s2][0], pb.v, o0);
;       o1 = MFMA(vf[sub][s2][1], pb.v, o1);
;     }
.Lmy_hm1361_1_np:
	s_waitcnt lgkmcnt(6)
	v_mfma_f32_32x32x16_bf16 v[26:41], v[62:65], v[78:81], v[26:41]
	v_mfma_f32_32x32x16_bf16 v[2:17], v[22:25], v[82:85], v[2:17]
	v_add3_u32 v22, v98, v177, v138
	s_waitcnt lgkmcnt(5)
	v_mfma_f32_32x32x16_bf16 v[26:41], v[66:69], v[82:85], v[26:41]
	v_mfma_f32_32x32x16_bf16 v[2:17], v[58:61], v[86:89], v[2:17]
	ds_read_b128 v[18:21], v0 offset:9216
	ds_read_b128 v[94:97], v0 offset:9248
	ds_read_b128 v[98:101], v22 offset:9216
	ds_read_b128 v[90:93], v22 offset:9248
	ds_read_b128 v[70:73], v0 offset:9280
	ds_read_b128 v[62:65], v0 offset:9312
	ds_read_b128 v[66:69], v22 offset:9280
	ds_read_b128 v[58:61], v22 offset:9312
	s_waitcnt lgkmcnt(12)
	v_mfma_f32_32x32x16_bf16 v[26:41], v[184:187], v[86:89], v[26:41]
	s_nop 1
	v_max3_f32 v0, v2, s8, v3
	v_max3_f32 v0, v0, v4, v5
	v_max3_f32 v0, v0, v6, v7
	v_max3_f32 v0, v0, v8, v9
	v_max3_f32 v0, v0, v10, v11
	v_max3_f32 v0, v0, v12, v13
	v_max3_f32 v0, v0, v14, v15
	v_max3_f32 v0, v0, v16, v17
	s_nop 1
	v_max3_f32 v0, v0, v26, v27
	v_max3_f32 v0, v0, v28, v29
	v_max3_f32 v0, v0, v30, v31
	v_max3_f32 v0, v0, v32, v33
	v_max3_f32 v0, v0, v34, v35
	v_max3_f32 v0, v0, v36, v37
	v_max3_f32 v0, v0, v38, v39
	v_max3_f32 v0, v0, v40, v41
	v_mul_f32_e32 v0, 0x3e38aa3b, v0
	v_max_f32_e32 v0, v149, v0
	ds_bpermute_b32 v22, v173, v0
	s_waitcnt lgkmcnt(0)
	v_max_f32_e32 v22, v22, v22
	v_max_f32_e32 v0, v0, v22
	v_fma_f32 v2, v2, s33, -v0
	v_fma_f32 v3, v3, s33, -v0
	v_exp_f32_e32 v23, v2
	v_fma_f32 v4, v4, s33, -v0
	v_exp_f32_e32 v24, v3
	v_fma_f32 v5, v5, s33, -v0
	v_exp_f32_e32 v25, v4
	v_exp_f32_e32 v149, v5
	v_fma_f32 v3, v6, s33, -v0
	v_add_f32_e32 v2, 0, v23
	v_exp_f32_e32 v150, v3
	v_fma_f32 v3, v7, s33, -v0
	v_add_f32_e32 v2, v24, v2
	v_exp_f32_e32 v151, v3
	v_fma_f32 v3, v8, s33, -v0
	v_add_f32_e32 v2, v25, v2
	v_exp_f32_e32 v174, v3
	v_fma_f32 v3, v9, s33, -v0
	v_add_f32_e32 v2, v149, v2
	v_exp_f32_e32 v178, v3
	v_fma_f32 v3, v10, s33, -v0
	v_add_f32_e32 v2, v150, v2
	v_exp_f32_e32 v183, v3
	v_fma_f32 v3, v11, s33, -v0
	v_add_f32_e32 v2, v151, v2
	v_exp_f32_e32 v184, v3
	v_fma_f32 v3, v12, s33, -v0
	v_add_f32_e32 v2, v174, v2
	v_exp_f32_e32 v185, v3
	v_fma_f32 v3, v13, s33, -v0
	v_add_f32_e32 v2, v178, v2
	v_exp_f32_e32 v186, v3
	v_fma_f32 v3, v14, s33, -v0
	v_add_f32_e32 v2, v183, v2
	v_exp_f32_e32 v187, v3
	v_fma_f32 v3, v15, s33, -v0
	v_add_f32_e32 v2, v184, v2
	v_exp_f32_e32 v188, v3
	v_fma_f32 v3, v16, s33, -v0
	v_add_f32_e32 v2, v185, v2
	v_exp_f32_e32 v189, v3
	v_fma_f32 v3, v17, s33, -v0
	v_add_f32_e32 v2, v186, v2
	v_exp_f32_e32 v190, v3
	v_fma_f32 v3, v26, s33, -v0
	v_add_f32_e32 v2, v187, v2
	v_exp_f32_e32 v191, v3
	v_fma_f32 v3, v27, s33, -v0
	v_add_f32_e32 v2, v188, v2
	v_exp_f32_e32 v194, v3
	v_fma_f32 v3, v28, s33, -v0
	v_add_f32_e32 v2, v189, v2
	v_exp_f32_e32 v195, v3
	v_fma_f32 v3, v29, s33, -v0
	v_add_f32_e32 v2, v190, v2
	v_exp_f32_e32 v196, v3
	v_fma_f32 v3, v30, s33, -v0
	v_add_f32_e32 v2, v191, v2
	v_exp_f32_e32 v197, v3
	v_fma_f32 v3, v31, s33, -v0
	v_add_f32_e32 v2, v194, v2
	v_exp_f32_e32 v198, v3
	v_fma_f32 v3, v32, s33, -v0
	v_add_f32_e32 v2, v195, v2
	v_exp_f32_e32 v199, v3
	v_sub_f32_e32 v22, v148, v0
	v_add_f32_e32 v2, v196, v2
	v_add_f32_e32 v2, v197, v2
	v_exp_f32_e32 v148, v22
	v_add_f32_e32 v2, v198, v2
	v_add_f32_e32 v200, v199, v2
	v_fma_f32 v2, v33, s33, -v0
	v_exp_f32_e32 v201, v2
	v_fma_f32 v2, v34, s33, -v0
	v_exp_f32_e32 v202, v2
	v_pk_mul_f32 v[16:17], v[144:145], v[148:149] op_sel_hi:[1,0]
	v_pk_mul_f32 v[14:15], v[140:141], v[148:149] op_sel_hi:[1,0]
	v_pk_mul_f32 v[12:13], v[132:133], v[148:149] op_sel_hi:[1,0]
	v_pk_mul_f32 v[10:11], v[130:131], v[148:149] op_sel_hi:[1,0]
	v_pk_mul_f32 v[8:9], v[128:129], v[148:149] op_sel_hi:[1,0]
	v_pk_mul_f32 v[6:7], v[126:127], v[148:149] op_sel_hi:[1,0]
	v_pk_mul_f32 v[4:5], v[124:125], v[148:149] op_sel_hi:[1,0]
	v_pk_mul_f32 v[2:3], v[122:123], v[148:149] op_sel_hi:[1,0]
	v_cvt_pk_bf16_f32 v122, v23, v24
	v_cvt_pk_bf16_f32 v123, v25, v149
	v_cvt_pk_bf16_f32 v124, v150, v151
	v_cvt_pk_bf16_f32 v125, v174, v178
	v_pk_mul_f32 v[32:33], v[142:143], v[148:149] op_sel_hi:[1,0]
	v_pk_mul_f32 v[30:31], v[120:121], v[148:149] op_sel_hi:[1,0]
	v_mfma_f32_32x32x16_bf16 v[2:17], v[18:21], v[122:125], v[2:17]
	v_mul_f32_e64 v28, v118, v148
	v_mul_f32_e64 v29, v119, v148
	v_mul_f32_e64 v26, v116, v148
	v_mul_f32_e64 v27, v117, v148
	v_mul_f32_e64 v24, v114, v148
	v_mul_f32_e64 v25, v115, v148
	v_pk_mul_f32 v[22:23], v[112:113], v[148:149] op_sel_hi:[1,0]
	v_pk_mul_f32 v[20:21], v[110:111], v[148:149] op_sel_hi:[1,0]
	v_pk_mul_f32 v[18:19], v[108:109], v[148:149] op_sel_hi:[1,0]
	v_fma_f32 v35, v35, s33, -v0
	v_add_f32_e32 v34, v201, v200
	v_mfma_f32_32x32x16_bf16 v[18:33], v[98:101], v[122:125], v[18:33]
	v_cvt_pk_bf16_f32 v98, v183, v184
	v_cvt_pk_bf16_f32 v99, v185, v186
	v_cvt_pk_bf16_f32 v100, v187, v188
	v_cvt_pk_bf16_f32 v101, v189, v190
	v_add_f32_e32 v34, v202, v34
	v_fma_f32 v39, v39, s33, -v0
	v_exp_f32_e32 v39, v39
	v_mfma_f32_32x32x16_bf16 v[2:17], v[94:97], v[98:101], v[2:17]
	v_exp_f32_e32 v94, v35
	v_fma_f32 v35, v36, s33, -v0
	v_exp_f32_e32 v95, v35
	v_fma_f32 v35, v37, s33, -v0
	v_exp_f32_e32 v96, v35
	v_add_f32_e32 v34, v94, v34
	v_add_f32_e32 v34, v95, v34
	v_mfma_f32_32x32x16_bf16 v[18:33], v[90:93], v[98:101], v[18:33]
	v_add_f32_e32 v90, v96, v34
	v_fma_f32 v34, v38, s33, -v0
	v_exp_f32_e32 v38, v34
	v_cvt_pk_bf16_f32 v34, v191, v194
	v_cvt_pk_bf16_f32 v35, v195, v196
	v_cvt_pk_bf16_f32 v36, v197, v198
	v_cvt_pk_bf16_f32 v37, v199, v201
	v_fma_f32 v40, v40, s33, -v0
	v_exp_f32_e32 v40, v40
	v_mfma_f32_32x32x16_bf16 v[2:17], v[70:73], v[34:37], v[2:17]
	v_fma_f32 v41, v41, s33, -v0
	v_exp_f32_e32 v41, v41
	v_add_f32_e32 v70, v38, v90
	v_mfma_f32_32x32x16_bf16 v[18:33], v[66:69], v[34:37], v[18:33]
	v_add_f32_e32 v34, v39, v70
	v_add_f32_e32 v34, v40, v34
	v_add_f32_e32 v66, v41, v34
	v_cvt_pk_bf16_f32 v34, v202, v94
	v_cvt_pk_bf16_f32 v35, v95, v96
	v_cvt_pk_bf16_f32 v36, v38, v39
	v_cvt_pk_bf16_f32 v37, v40, v41
	s_nop 1
	v_mfma_f32_32x32x16_bf16 v[2:17], v[62:65], v[34:37], v[2:17]
	v_mfma_f32_32x32x16_bf16 v[18:33], v[58:61], v[34:37], v[18:33]
	v_fma_f32 v40, v147, v148, v66

; #define MFMA(a, b, c) __builtin_amdgcn_mfma_f32_32x32x16_bf16((a), (b), (c), 0, 0, 0)
; template <int DQK, bool MASKED, int MODE, class MF>
; DI void attn_step(const bf16_t* sK, const bf16_t* sVt, const bf16x8 (&qf)[DQK / 16], f32x16& o0, f32x16& o1, float& m, float& l,
;                   float sc, const MF& mf, int lane, f32x16 (&s)[2], float invl, bool lanevalid = true) {
;     ...
;   bf16x8 kf[2][DQK / 16];
; #pragma unroll
;   for (int sub = 0; sub < 2; ++sub)
; #pragma unroll
;     for (int ks = 0; ks < DQK / 16; ++ks) kf[sub][ks] = *(const bf16x8*)(sK + (sub * 32 + pr) * KST + ks * 16 + 8 * h);
;   __builtin_amdgcn_sched_barrier(0);
; #pragma unroll
;   for (int q = 0; q < 16; ++q) { s[0][q] = 0.f; s[1][q] = 0.f; }
; #pragma unroll
;   for (int ks = 0; ks < DQK / 16; ++ks) {
;     s[0] = MFMA(kf[0][ks], qf[ks], s[0]);
;     s[1] = MFMA(kf[1][ks], qf[ks], s[1]);
;   }
; DI void phase_attn_swa(const Params& P, const float* sinks, bf16_t* og, unsigned char* smem, int L, int G) {
;     ...
;     for (int j = jlo; j <= jhi; ++j) {
;       const int key0 = j * 64, cb = (j - jlo) & 1;
;       __syncthreads();
;       if (j < jhi) kv64_store(R, sK + (cb ^ 1) * KVB64, sVt + (cb ^ 1) * KVB64, tid);
;       if (j + 1 < jhi) kv64_fetch(R, kb, 256, vb, SEQ, key0 + 128, true, tid);
;       __builtin_amdgcn_sched_barrier(0);
;       auto mf = [&](int kk) { const int key = key0 + kk; return key <= t && key > t - 128; };
;       attn_step<64, true, 0>(sK + cb * KVB64, sVt + cb * KVB64, qf, o0, o1, m, l, sc, mf, lane, s, 0.f);
.LBB0_1668:
	s_add_i32 s1, s17, s18
	s_and_b32 s0, s18, 1
	s_cmp_ge_u32 s1, s11
	s_cselect_b32 s99, 0, 1
	s_add_i32 s1, s1, 1
	s_cmp_ge_u32 s1, s11
	s_cselect_b32 s98, 0, 2
	s_or_b32 s99, s99, s98
	s_xor_b32 s98, s0, 1
	s_mulk_i32 s98, 0x4800
	s_waitcnt lgkmcnt(0)
	s_barrier

; template <int DQK, bool MASKED, int MODE, class MF>
; DI void attn_step(const bf16_t* sK, const bf16_t* sVt, const bf16x8 (&qf)[DQK / 16], f32x16& o0, f32x16& o1, float& m, float& l,
;                   float sc, const MF& mf, int lane, f32x16 (&s)[2], float invl, bool lanevalid = true) {
;     ...
;   bf16x8 vf[2][2][2];
;   if (MODE != 1) {
; #pragma unroll
;     for (int sub = 0; sub < 2; ++sub)
; #pragma unroll
;       for (int s2 = 0; s2 < 2; ++s2) {
;         vf[sub][s2][0] = *(const bf16x8*)(sVt + r * 72 + sub * 32 + s2 * 16 + 8 * h);
;         vf[sub][s2][1] = *(const bf16x8*)(sVt + (32 + r) * 72 + sub * 32 + s2 * 16 + 8 * h);
;       }
;     __builtin_amdgcn_sched_barrier(0);
;   }
;   float mxr = -3.0e38f;
; #pragma unroll
;   for (int sub = 0; sub < 2; ++sub)
; #pragma unroll
;     for (int q = 0; q < 16; ++q) {
;       if (MASKED) { const int kk = sub * 32 + 16 * (q >> 3) + 8 * h + (q & 7); s[sub][q] = mf(kk) ? s[sub][q] : -3.0e38f; }
;       if (MODE != 2) mxr = fmaxf(mxr, s[sub][q]);
;     }
.Lmy_hm1668_0_sd:
	s_bitcmp1_b32 s99, 1
	s_cbranch_scc0 .Lmy_hm1668_0_np
	v_mov_b32_e32 v253, 0
	v_add_u32_e32 v250, s8, v158
	v_add_u32_e32 v252, 0x80, v250
	v_lshlrev_b64 v[248:249], 9, v[252:253]
	v_add_u32_e32 v252, 0xa0, v250
	v_lshl_add_u64 v[248:249], v[152:153], 0, v[248:249]
	v_lshlrev_b64 v[250:251], 9, v[252:253]
	s_lshl_b64 s[100:101], s[8:9], 1
	v_lshl_add_u64 v[250:251], v[152:153], 0, v[250:251]
	global_load_dwordx4 v[80:83], v[248:249], off
	global_load_dwordx4 v[84:87], v[250:251], off
	v_lshl_add_u64 v[248:249], v[154:155], 0, s[100:101]
	v_lshl_add_u64 v[250:251], v[156:157], 0, s[100:101]
	global_load_dwordx4 v[88:91], v[248:249], off offset:256
	global_load_dwordx4 v[92:95], v[250:251], off offset:256
.Lmy_hm1668_0_np:
	s_waitcnt lgkmcnt(6)
	v_mfma_f32_32x32x16_bf16 v[32:47], v[108:111], v[68:71], v[32:47]
	v_mfma_f32_32x32x16_bf16 v[48:63], v[100:103], v[72:75], v[48:63]
	s_waitcnt lgkmcnt(5)
	v_mfma_f32_32x32x16_bf16 v[32:47], v[112:115], v[72:75], v[32:47]
	v_mfma_f32_32x32x16_bf16 v[48:63], v[104:107], v[76:79], v[48:63]
	ds_read_b128 v[124:127], v96 offset:9216
	ds_read_b128 v[116:119], v96 offset:9248
	ds_read_b128 v[120:123], v97 offset:9216
	ds_read_b128 v[112:115], v97 offset:9248
	ds_read_b128 v[108:111], v96 offset:9280
	ds_read_b128 v[100:103], v96 offset:9312
	ds_read_b128 v[104:107], v97 offset:9280
	ds_read_b128 v[96:99], v97 offset:9312
	s_waitcnt lgkmcnt(12)
	v_mfma_f32_32x32x16_bf16 v[32:47], v[178:181], v[76:79], v[32:47]
	v_add_u32_e32 v128, s8, v162
	v_cmp_le_u32_e32 vcc, v128, v150
	v_cmp_gt_i32_e64 s[0:1], v128, v151
	s_and_b64 vcc, vcc, s[0:1]
	v_cndmask_b32_e32 v48, v172, v48, vcc
	v_cmp_lt_u32_e32 vcc, v128, v150
	v_cmp_ge_i32_e64 s[0:1], v128, v151
	s_and_b64 vcc, vcc, s[0:1]
	v_add_u32_e32 v177, 2, v128
	v_cndmask_b32_e32 v49, v172, v49, vcc
	v_cmp_le_u32_e32 vcc, v177, v150
	v_cmp_gt_i32_e64 s[0:1], v177, v151
	s_and_b64 vcc, vcc, s[0:1]
	v_add_u32_e32 v177, 3, v128
	v_cndmask_b32_e32 v50, v172, v50, vcc
	v_cmp_le_u32_e32 vcc, v177, v150
	v_cmp_gt_i32_e64 s[0:1], v177, v151
	s_and_b64 vcc, vcc, s[0:1]
	v_add_u32_e32 v177, 4, v128
	v_cndmask_b32_e32 v51, v172, v51, vcc
	v_cmp_le_u32_e32 vcc, v177, v150
	v_cmp_gt_i32_e64 s[0:1], v177, v151
	s_and_b64 vcc, vcc, s[0:1]
	v_add_u32_e32 v177, 5, v128
	v_cndmask_b32_e32 v52, v172, v52, vcc
	v_cmp_le_u32_e32 vcc, v177, v150
	v_cmp_gt_i32_e64 s[0:1], v177, v151
	s_and_b64 vcc, vcc, s[0:1]
	v_add_u32_e32 v177, 6, v128
	v_cndmask_b32_e32 v53, v172, v53, vcc
	v_cmp_le_u32_e32 vcc, v177, v150
	v_cmp_gt_i32_e64 s[0:1], v177, v151
	v_add_u32_e32 v177, s8, v161
	s_and_b64 vcc, vcc, s[0:1]
	v_or_b32_e32 v178, 7, v177
	v_cndmask_b32_e32 v54, v172, v54, vcc
	v_cmp_le_u32_e32 vcc, v178, v150
	v_cmp_gt_i32_e64 s[0:1], v178, v151
	s_and_b64 vcc, vcc, s[0:1]
	v_add_u32_e32 v178, 16, v128
	v_cndmask_b32_e32 v55, v172, v55, vcc
	v_cmp_le_u32_e32 vcc, v178, v150
	v_cmp_gt_i32_e64 s[0:1], v178, v151
	s_and_b64 vcc, vcc, s[0:1]
	v_add_u32_e32 v178, 17, v128
	v_cndmask_b32_e32 v56, v172, v56, vcc
	v_cmp_le_u32_e32 vcc, v178, v150
	v_cmp_gt_i32_e64 s[0:1], v178, v151
	s_and_b64 vcc, vcc, s[0:1]
	v_add_u32_e32 v178, 18, v128
	v_cndmask_b32_e32 v57, v172, v57, vcc
	v_cmp_le_u32_e32 vcc, v178, v150
	v_cmp_gt_i32_e64 s[0:1], v178, v151
	s_and_b64 vcc, vcc, s[0:1]
	v_add_u32_e32 v178, 19, v128
	v_cndmask_b32_e32 v58, v172, v58, vcc
	v_cmp_le_u32_e32 vcc, v178, v150
	v_cmp_gt_i32_e64 s[0:1], v178, v151
	s_and_b64 vcc, vcc, s[0:1]
	v_add_u32_e32 v178, 20, v128
	v_cndmask_b32_e32 v59, v172, v59, vcc
	v_cmp_le_u32_e32 vcc, v178, v150
	v_cmp_gt_i32_e64 s[0:1], v178, v151
	s_and_b64 vcc, vcc, s[0:1]
	v_add_u32_e32 v178, 21, v128
	v_cndmask_b32_e32 v60, v172, v60, vcc
	v_cmp_le_u32_e32 vcc, v178, v150
	v_cmp_gt_i32_e64 s[0:1], v178, v151
	s_and_b64 vcc, vcc, s[0:1]
	v_add_u32_e32 v178, 22, v128
	v_cndmask_b32_e32 v61, v172, v61, vcc
	v_cmp_le_u32_e32 vcc, v178, v150
	v_cmp_gt_i32_e64 s[0:1], v178, v151
	s_and_b64 vcc, vcc, s[0:1]
	v_or_b32_e32 v178, 23, v177
	v_cndmask_b32_e32 v62, v172, v62, vcc
	v_cmp_le_u32_e32 vcc, v178, v150
	v_cmp_gt_i32_e64 s[0:1], v178, v151
	s_and_b64 vcc, vcc, s[0:1]
	v_add_u32_e32 v178, 32, v128
	v_cndmask_b32_e32 v63, v172, v63, vcc
	v_cmp_le_u32_e32 vcc, v178, v150
	v_cmp_gt_i32_e64 s[0:1], v178, v151
	s_and_b64 vcc, vcc, s[0:1]
	v_cndmask_b32_e32 v178, v172, v32, vcc
	v_add_u32_e32 v32, 33, v128
	v_cmp_le_u32_e32 vcc, v32, v150
	v_cmp_gt_i32_e64 s[0:1], v32, v151
	s_and_b64 vcc, vcc, s[0:1]
	v_add_u32_e32 v32, 34, v128
	v_cndmask_b32_e32 v33, v172, v33, vcc
	v_cmp_le_u32_e32 vcc, v32, v150
	v_cmp_gt_i32_e64 s[0:1], v32, v151
	s_and_b64 vcc, vcc, s[0:1]
	v_add_u32_e32 v32, 35, v128
	v_cndmask_b32_e32 v34, v172, v34, vcc
	v_cmp_le_u32_e32 vcc, v32, v150
	v_cmp_gt_i32_e64 s[0:1], v32, v151
	s_and_b64 vcc, vcc, s[0:1]
	v_add_u32_e32 v32, 36, v128
	v_cndmask_b32_e32 v35, v172, v35, vcc
	v_cmp_le_u32_e32 vcc, v32, v150
	v_cmp_gt_i32_e64 s[0:1], v32, v151
	s_and_b64 vcc, vcc, s[0:1]
	v_add_u32_e32 v32, 37, v128
	v_cndmask_b32_e32 v36, v172, v36, vcc
	v_cmp_le_u32_e32 vcc, v32, v150
	v_cmp_gt_i32_e64 s[0:1], v32, v151
	s_and_b64 vcc, vcc, s[0:1]
	v_add_u32_e32 v32, 38, v128
	v_cndmask_b32_e32 v37, v172, v37, vcc
	v_cmp_le_u32_e32 vcc, v32, v150
	v_cmp_gt_i32_e64 s[0:1], v32, v151
	s_and_b64 vcc, vcc, s[0:1]
	v_or_b32_e32 v32, 39, v177
	v_cndmask_b32_e32 v38, v172, v38, vcc
	v_cmp_le_u32_e32 vcc, v32, v150
	v_cmp_gt_i32_e64 s[0:1], v32, v151
	s_and_b64 vcc, vcc, s[0:1]
	v_add_u32_e32 v32, 48, v128
	v_cndmask_b32_e32 v39, v172, v39, vcc
	v_cmp_le_u32_e32 vcc, v32, v150
	v_cmp_gt_i32_e64 s[0:1], v32, v151
	s_and_b64 vcc, vcc, s[0:1]
	v_add_u32_e32 v32, 49, v128
; #define MFMA(a, b, c) __builtin_amdgcn_mfma_f32_32x32x16_bf16((a), (b), (c), 0, 0, 0)
; DI unsigned pack2(float a, float b) { f32x2_t v = {a, b}; bf16x2_t r = __builtin_convertvector(v, bf16x2_t); return __builtin_bit_cast(unsigned, r); }
; DI float fexp2(float x) { return __builtin_amdgcn_exp2f(x); }
; DI float shx(float v, int m) { return __shfl_xor(v, m, 64); }
; template <int DQK, bool MASKED, int MODE, class MF>
; DI void attn_step(const bf16_t* sK, const bf16_t* sVt, const bf16x8 (&qf)[DQK / 16], f32x16& o0, f32x16& o1, float& m, float& l,
;                   float sc, const MF& mf, int lane, f32x16 (&s)[2], float invl, bool lanevalid = true) {
;     ...
;   float mxr = -3.0e38f;
; #pragma unroll
;   for (int sub = 0; sub < 2; ++sub)
; #pragma unroll
;     for (int q = 0; q < 16; ++q) {
;       if (MASKED) { const int kk = sub * 32 + 16 * (q >> 3) + 8 * h + (q & 7); s[sub][q] = mf(kk) ? s[sub][q] : -3.0e38f; }
;       if (MODE != 2) mxr = fmaxf(mxr, s[sub][q]);
;     }
;   float alpha = 1.f;
;   if (MODE != 2) {
;     float mx = fmaxf(m, mxr * sc);
;     mx = fmaxf(mx, shx(mx, 32));
;     if (!MASKED) mx = lanevalid ? mx : m;
;     alpha = fexp2(m - mx);
;     m = mx;
;   }
;   const float moff = (!MASKED && !lanevalid) ? 1.0e30f : m;
;   float ps = 0.f;
; #pragma unroll
;   for (int sub = 0; sub < 2; ++sub)
; #pragma unroll
;     for (int q = 0; q < 16; ++q) {
;       float pv = fexp2(__builtin_fmaf(s[sub][q], sc, -moff));
;       if (MASKED && MODE != 0) pv = (s[sub][q] > -1.0e38f) ? pv : 0.f;
;       if (MODE == 2) pv *= invl;
;       s[sub][q] = pv;
;       ps += pv;
;     }
;   if (MODE != 2) {
;     ps += shx(ps, 32);
;     l = l * alpha + ps;
;   }
;   if (MODE == 1) return;
;   if (MODE == 0) {
; #pragma unroll
;     for (int q = 0; q < 16; ++q) { o0[q] *= alpha; o1[q] *= alpha; }
;   }
; #pragma unroll
;   for (int sub = 0; sub < 2; ++sub)
; #pragma unroll
;     for (int s2 = 0; s2 < 2; ++s2) {
;       union { bf16x8 v; unsigned u[4]; } pb;
; #pragma unroll
;       for (int e = 0; e < 4; ++e) pb.u[e] = pack2(s[sub][8 * s2 + 2 * e], s[sub][8 * s2 + 2 * e + 1]);
;       o0 = MFMA(vf[sub][s2][0], pb.v, o0);
;       o1 = MFMA(vf[sub][s2][1], pb.v, o1);
;     }
	v_cndmask_b32_e32 v179, v172, v40, vcc
	v_cmp_le_u32_e32 vcc, v32, v150
	v_cmp_gt_i32_e64 s[0:1], v32, v151
	s_and_b64 vcc, vcc, s[0:1]
	v_add_u32_e32 v32, 50, v128
	v_cndmask_b32_e32 v41, v172, v41, vcc
	v_cmp_le_u32_e32 vcc, v32, v150
	v_cmp_gt_i32_e64 s[0:1], v32, v151
	s_and_b64 vcc, vcc, s[0:1]
	v_add_u32_e32 v32, 51, v128
	v_cndmask_b32_e32 v42, v172, v42, vcc
	v_cmp_le_u32_e32 vcc, v32, v150
	v_cmp_gt_i32_e64 s[0:1], v32, v151
	s_and_b64 vcc, vcc, s[0:1]
	v_add_u32_e32 v32, 52, v128
	v_cndmask_b32_e32 v43, v172, v43, vcc
	v_cmp_le_u32_e32 vcc, v32, v150
	v_cmp_gt_i32_e64 s[0:1], v32, v151
	s_and_b64 vcc, vcc, s[0:1]
	v_add_u32_e32 v32, 53, v128
	v_cndmask_b32_e32 v44, v172, v44, vcc
	v_cmp_le_u32_e32 vcc, v32, v150
	v_cmp_gt_i32_e64 s[0:1], v32, v151
	s_and_b64 vcc, vcc, s[0:1]
	v_add_u32_e32 v32, 54, v128
	v_cndmask_b32_e32 v45, v172, v45, vcc
	v_cmp_le_u32_e32 vcc, v32, v150
	v_cmp_gt_i32_e64 s[0:1], v32, v151
	s_and_b64 vcc, vcc, s[0:1]
	v_or_b32_e32 v32, 55, v177
	v_cndmask_b32_e32 v46, v172, v46, vcc
	v_cmp_le_u32_e32 vcc, v32, v150
	v_cmp_gt_i32_e64 s[0:1], v32, v151
	v_max3_f32 v32, v48, s14, v49
	v_max3_f32 v32, v32, v50, v51
	v_max3_f32 v32, v32, v52, v53
	v_max3_f32 v32, v32, v54, v55
	v_max3_f32 v32, v32, v56, v57
	v_max3_f32 v32, v32, v58, v59
	v_max3_f32 v32, v32, v60, v61
	v_max3_f32 v32, v32, v62, v63
	v_max3_f32 v32, v32, v178, v33
	v_max3_f32 v32, v32, v34, v35
	v_max3_f32 v32, v32, v36, v37
	v_max3_f32 v32, v32, v38, v39
	v_max3_f32 v32, v32, v179, v41
	s_and_b64 vcc, vcc, s[0:1]
	v_max3_f32 v32, v32, v42, v43
	v_cndmask_b32_e32 v47, v172, v47, vcc
	v_max3_f32 v32, v32, v44, v45
	v_max3_f32 v32, v32, v46, v47
	v_mul_f32_e32 v32, 0x3e38aa3b, v32
	v_max_f32_e32 v40, v176, v176
	v_max_f32_e32 v32, v40, v32
	ds_bpermute_b32 v40, v174, v32
	s_add_i32 s18, s18, 1
	s_add_i32 s0, s17, s18
	s_add_i32 s8, s8, 64
	s_add_i32 s0, s0, -1
	s_waitcnt lgkmcnt(0)
	v_max_f32_e32 v40, v40, v40
	v_max_f32_e32 v32, v32, v40
	v_fma_f32 v40, v48, s15, -v32
	v_exp_f32_e32 v48, v40
	v_fma_f32 v49, v49, s15, -v32
	v_exp_f32_e32 v49, v49
	v_fma_f32 v50, v50, s15, -v32
	v_exp_f32_e32 v50, v50
	v_fma_f32 v51, v51, s15, -v32
	v_exp_f32_e32 v51, v51
	v_fma_f32 v52, v52, s15, -v32
	v_add_f32_e32 v128, 0, v48
	v_exp_f32_e32 v52, v52
	v_fma_f32 v53, v53, s15, -v32
	v_add_f32_e32 v128, v49, v128
	v_exp_f32_e32 v53, v53
	v_fma_f32 v54, v54, s15, -v32
	v_add_f32_e32 v128, v50, v128
	v_exp_f32_e32 v54, v54
	v_fma_f32 v55, v55, s15, -v32
	v_add_f32_e32 v128, v51, v128
	v_exp_f32_e32 v55, v55
	v_fma_f32 v56, v56, s15, -v32
	v_add_f32_e32 v128, v52, v128
	v_exp_f32_e32 v56, v56
	v_fma_f32 v57, v57, s15, -v32
	v_add_f32_e32 v128, v53, v128
	v_exp_f32_e32 v57, v57
	v_fma_f32 v58, v58, s15, -v32
	v_add_f32_e32 v128, v54, v128
	v_exp_f32_e32 v58, v58
	v_fma_f32 v59, v59, s15, -v32
	v_add_f32_e32 v128, v55, v128
	v_exp_f32_e32 v59, v59
	v_fma_f32 v60, v60, s15, -v32
	v_add_f32_e32 v128, v56, v128
	v_exp_f32_e32 v60, v60
	v_fma_f32 v61, v61, s15, -v32
	v_add_f32_e32 v128, v57, v128
	v_exp_f32_e32 v61, v61
	v_fma_f32 v62, v62, s15, -v32
	v_add_f32_e32 v128, v58, v128
	v_exp_f32_e32 v62, v62
	v_fma_f32 v63, v63, s15, -v32
	v_sub_f32_e32 v40, v176, v32
	v_add_f32_e32 v128, v59, v128
	v_exp_f32_e32 v63, v63
	v_fma_f32 v176, v178, s15, -v32
	v_add_f32_e32 v128, v60, v128
	v_exp_f32_e32 v176, v176
	v_fma_f32 v33, v33, s15, -v32
	v_add_f32_e32 v128, v61, v128
	v_exp_f32_e32 v33, v33
	v_fma_f32 v34, v34, s15, -v32
	v_add_f32_e32 v128, v62, v128
	v_exp_f32_e32 v177, v34
	v_fma_f32 v34, v35, s15, -v32
	v_add_f32_e32 v128, v63, v128
	v_exp_f32_e32 v178, v34
	v_fma_f32 v34, v36, s15, -v32
	v_add_f32_e32 v128, v176, v128
	v_exp_f32_e32 v180, v34
	v_fma_f32 v35, v37, s15, -v32
	v_add_f32_e32 v34, v33, v128
	v_exp_f32_e32 v128, v35
	v_fma_f32 v35, v38, s15, -v32
	v_add_f32_e32 v34, v177, v34
	v_exp_f32_e32 v38, v35
	v_fma_f32 v35, v39, s15, -v32
	v_add_f32_e32 v34, v178, v34
	v_exp_f32_e32 v39, v35
	v_add_f32_e32 v34, v180, v34
	v_exp_f32_e32 v40, v40
	v_add_f32_e32 v34, v128, v34
	v_add_f32_e32 v34, v38, v34
	v_add_f32_e32 v181, v39, v34
	v_fma_f32 v34, v179, s15, -v32
	v_exp_f32_e32 v179, v34
	v_pk_mul_f32 v[14:15], v[14:15], v[40:41] op_sel_hi:[1,0]
	v_pk_mul_f32 v[12:13], v[12:13], v[40:41] op_sel_hi:[1,0]
	v_pk_mul_f32 v[10:11], v[10:11], v[40:41] op_sel_hi:[1,0]
	v_pk_mul_f32 v[8:9], v[8:9], v[40:41] op_sel_hi:[1,0]
	v_pk_mul_f32 v[6:7], v[6:7], v[40:41] op_sel_hi:[1,0]
	v_pk_mul_f32 v[4:5], v[4:5], v[40:41] op_sel_hi:[1,0]
	v_pk_mul_f32 v[2:3], v[2:3], v[40:41] op_sel_hi:[1,0]
	v_pk_mul_f32 v[0:1], v[0:1], v[40:41] op_sel_hi:[1,0]
	v_pk_mul_f32 v[30:31], v[30:31], v[40:41] op_sel_hi:[1,0]
	v_cvt_pk_bf16_f32 v34, v48, v49
	v_cvt_pk_bf16_f32 v35, v50, v51
	v_cvt_pk_bf16_f32 v36, v52, v53
	v_cvt_pk_bf16_f32 v37, v54, v55
	v_pk_mul_f32 v[28:29], v[28:29], v[40:41] op_sel_hi:[1,0]
	v_pk_mul_f32 v[26:27], v[26:27], v[40:41] op_sel_hi:[1,0]
	v_pk_mul_f32 v[24:25], v[24:25], v[40:41] op_sel_hi:[1,0]
	v_pk_mul_f32 v[22:23], v[22:23], v[40:41] op_sel_hi:[1,0]
	v_pk_mul_f32 v[20:21], v[20:21], v[40:41] op_sel_hi:[1,0]
	v_pk_mul_f32 v[18:19], v[18:19], v[40:41] op_sel_hi:[1,0]
	v_pk_mul_f32 v[16:17], v[16:17], v[40:41] op_sel_hi:[1,0]
	v_mfma_f32_32x32x16_bf16 v[0:15], v[124:127], v[34:37], v[0:15]
	v_fma_f32 v42, v42, s15, -v32
	v_exp_f32_e32 v42, v42
	v_fma_f32 v43, v43, s15, -v32
	v_exp_f32_e32 v43, v43
	v_fma_f32 v44, v44, s15, -v32
	v_add_f32_e32 v48, v179, v181
	v_exp_f32_e32 v44, v44
	v_mfma_f32_32x32x16_bf16 v[16:31], v[120:123], v[34:37], v[16:31]
	v_fma_f32 v34, v41, s15, -v32
	v_exp_f32_e32 v41, v34
	v_cvt_pk_bf16_f32 v34, v56, v57
	v_cvt_pk_bf16_f32 v35, v58, v59
	v_cvt_pk_bf16_f32 v36, v60, v61
	v_cvt_pk_bf16_f32 v37, v62, v63
	v_add_f32_e32 v48, v41, v48
	s_cmp_ge_u32 s0, s11
	v_mfma_f32_32x32x16_bf16 v[0:15], v[116:119], v[34:37], v[0:15]
	v_mfma_f32_32x32x16_bf16 v[16:31], v[112:115], v[34:37], v[16:31]
	v_add_f32_e32 v34, v42, v48
	v_add_f32_e32 v34, v43, v34
	v_add_f32_e32 v48, v44, v34
	v_cvt_pk_bf16_f32 v34, v176, v33
	v_cvt_pk_bf16_f32 v35, v177, v178
	v_cvt_pk_bf16_f32 v36, v180, v128
	v_cvt_pk_bf16_f32 v37, v38, v39
	v_fma_f32 v33, v45, s15, -v32
	v_fma_f32 v38, v46, s15, -v32
	v_mfma_f32_32x32x16_bf16 v[0:15], v[108:111], v[34:37], v[0:15]
	v_exp_f32_e32 v33, v33
	v_exp_f32_e32 v39, v38
	v_fma_f32 v38, v47, s15, -v32
	v_exp_f32_e32 v45, v38
	v_add_f32_e32 v38, v33, v48
	v_mfma_f32_32x32x16_bf16 v[16:31], v[104:107], v[34:37], v[16:31]
	v_add_f32_e32 v34, v39, v38
	v_cvt_pk_bf16_f32 v36, v179, v41
	v_cvt_pk_bf16_f32 v37, v42, v43
	v_cvt_pk_bf16_f32 v38, v44, v33
	v_cvt_pk_bf16_f32 v39, v39, v45
	v_add_f32_e32 v34, v45, v34
	ds_bpermute_b32 v35, v174, v34
	v_mfma_f32_32x32x16_bf16 v[0:15], v[100:103], v[36:39], v[0:15]
	s_waitcnt lgkmcnt(0)
	v_add_f32_e32 v34, v34, v35
	v_fmac_f32_e32 v34, v175, v40
	v_mfma_f32_32x32x16_bf16 v[16:31], v[96:99], v[36:39], v[16:31]
	s_cbranch_scc1 .LBB0_1659
	v_mov_b32_e32 v175, v34
	v_mov_b32_e32 v176, v32
	s_branch .LBB0_1668
